# SwiGLU epilogue (P2,P9) rewritten with packed f32 mul/add (same ops, same order), batch of 8 pairs per stage
# baseline (speedup 1.0000x reference)
; #define PG8_STAGE(bufoff, gbase, voff) do { _Pragma("unroll") for (int _i = 0; _i < 2; ++_i) \
;         __builtin_amdgcn_global_load_lds((const unsigned*)((const char*)(gbase) + (voff)[_i]), (LAS unsigned*)(lds + (bufoff) + ldsw + _i * 8192), 16, 0, 0); } while (0)
; #define PG8_LDA(dst, b, h) do { _Pragma("unroll") for (int m = 0; m < 4; ++m) _Pragma("unroll") for (int k = 0; k < 2; ++k) dst[m][k] = *(const LAS bf16x8*)(lds + PG8_SA(b, h) + aoff + m * 2048 + k * 1024); } while (0)
; #define PG8_LDB(dst, b, h) do { _Pragma("unroll") for (int n = 0; n < 2; ++n) _Pragma("unroll") for (int k = 0; k < 2; ++k) dst[n][k] = *(const LAS bf16x8*)(lds + PG8_SB(b, h) + boff + n * 2048 + k * 1024); } while (0)
; #define PG8_MMA(ai, bj, At, Bt) do { __builtin_amdgcn_s_setprio(1); _Pragma("unroll") for (int m = 0; m < 4; ++m) _Pragma("unroll") for (int n = 0; n < 2; ++n) _Pragma("unroll") for (int k = 0; k < 2; ++k) \
;         acc[ai][bj][m][n] = __builtin_amdgcn_mfma_f32_16x16x32_bf16(Bt[n][k], At[m][k], acc[ai][bj][m][n], 0, 0, 0); __builtin_amdgcn_s_setprio(0); } while (0)
; #define PG8_WAIT_L(n) asm volatile("s_waitcnt lgkmcnt(" #n ")" ::: "memory")
; #define PG8_BAR __builtin_amdgcn_s_barrier()
; #define PG8_SCHED __builtin_amdgcn_sched_barrier(0)
; template <class Epi, class Sched>
; __device__ __forceinline__ void gemm_phase(LAS unsigned char* lds, const Gemm g, const Sched& S, const Epi& E) {
;     ...
;             PG8_LDB(B0, 0, 0); PG8_SCHED; PG8_LDA(At, 0, 0); PG8_STAGE(PG8_SA(1, 1), a1 + hstep, voffA);
;             PG8_WAIT_L(8); PG8_BAR; PG8_WAIT_L(0); PG8_MMA(0, 0, At, B0); PG8_BAR; PG8_SCHED;
;             PG8_LDB(B1, 0, 1); PG8_STAGE(PG8_SB(0, 0), b2, voffB);
;             PG8_BAR; PG8_WAIT_L(0); PG8_MMA(0, 1, At, B1); PG8_BAR;
;             PG8_LDA(At, 0, 1); PG8_STAGE(PG8_SA(0, 0), a2, voffA);
;             PG8_BAR; PG8_WAIT_L(0); PG8_MMA(1, 0, At, B0); PG8_BAR; PG8_SCHED;
.LBB0_235:
	ds_read_b128 v[150:153], v147
	ds_read_b128 v[154:157], v147 offset:1024
	ds_read_b128 v[158:161], v147 offset:2048
	ds_read_b128 v[162:165], v147 offset:3072
	s_add_u32 s16, s14, 0xfffc0080
	s_addc_u32 s17, s15, -1
	s_cmp_eq_u32 s48, 12
	s_cselect_b32 s23, s7, s17
	s_cselect_b32 s22, s44, s16
	s_cselect_b32 s19, s5, s47
	s_cselect_b32 s18, s45, s46
	v_lshl_add_u64 v[198:199], s[14:15], 0, v[136:137]
	s_add_i32 m0, s13, 0xc000
	ds_read_b128 v[166:169], v148
	ds_read_b128 v[170:173], v148 offset:1024
	ds_read_b128 v[174:177], v148 offset:2048
	ds_read_b128 v[178:181], v148 offset:3072
	ds_read_b128 v[182:185], v148 offset:4096
	ds_read_b128 v[186:189], v148 offset:5120
	ds_read_b128 v[190:193], v148 offset:6144
	ds_read_b128 v[194:197], v148 offset:7168
	global_load_lds_dwordx4 v[198:199], off
	v_lshl_add_u64 v[198:199], s[14:15], 0, v[138:139]
	s_add_i32 m0, s13, 0xe000
	s_nop 0
	global_load_lds_dwordx4 v[198:199], off
	s_waitcnt lgkmcnt(8)
	s_barrier
	s_waitcnt lgkmcnt(0)
	s_setprio 1
	s_waitcnt lgkmcnt(0)
	v_mfma_f32_16x16x32_bf16 v[124:127], v[150:153], v[166:169], v[124:127]
	v_mfma_f32_16x16x32_bf16 v[116:119], v[158:161], v[166:169], v[116:119]
	v_mfma_f32_16x16x32_bf16 v[108:111], v[150:153], v[174:177], v[108:111]
	v_mfma_f32_16x16x32_bf16 v[100:103], v[158:161], v[174:177], v[100:103]
	v_mfma_f32_16x16x32_bf16 v[92:95], v[150:153], v[182:185], v[92:95]
	v_mfma_f32_16x16x32_bf16 v[84:87], v[158:161], v[182:185], v[84:87]
	v_mfma_f32_16x16x32_bf16 v[76:79], v[150:153], v[190:193], v[76:79]
	v_mfma_f32_16x16x32_bf16 v[68:71], v[158:161], v[190:193], v[68:71]
	v_mfma_f32_16x16x32_bf16 v[124:127], v[154:157], v[170:173], v[124:127]
	v_mfma_f32_16x16x32_bf16 v[116:119], v[162:165], v[170:173], v[116:119]
	v_mfma_f32_16x16x32_bf16 v[108:111], v[154:157], v[178:181], v[108:111]
	v_mfma_f32_16x16x32_bf16 v[100:103], v[162:165], v[178:181], v[100:103]
	v_mfma_f32_16x16x32_bf16 v[92:95], v[154:157], v[186:189], v[92:95]
	v_mfma_f32_16x16x32_bf16 v[84:87], v[162:165], v[186:189], v[84:87]
	v_mfma_f32_16x16x32_bf16 v[76:79], v[154:157], v[194:197], v[76:79]
	v_mfma_f32_16x16x32_bf16 v[68:71], v[162:165], v[194:197], v[68:71]
	s_setprio 0
	s_barrier
	s_add_i32 s16, s40, s25
	v_lshl_add_u64 v[198:199], s[18:19], 0, v[132:133]
	s_mov_b32 m0, s16
	ds_read_b128 v[202:205], v149
	ds_read_b128 v[206:209], v149 offset:1024
	ds_read_b128 v[210:213], v149 offset:2048
	ds_read_b128 v[214:217], v149 offset:3072
	global_load_lds_dwordx4 v[198:199], off
	v_lshl_add_u64 v[218:219], s[18:19], 0, v[128:129]
	s_add_i32 m0, s16, 0x2000
	s_nop 0
	global_load_lds_dwordx4 v[218:219], off
	s_barrier
	s_waitcnt lgkmcnt(0)
	s_setprio 1
	s_waitcnt lgkmcnt(0)
	v_mfma_f32_16x16x32_bf16 v[120:123], v[202:205], v[166:169], v[120:123]
	v_mfma_f32_16x16x32_bf16 v[112:115], v[210:213], v[166:169], v[112:115]
	v_mfma_f32_16x16x32_bf16 v[104:107], v[202:205], v[174:177], v[104:107]
	v_mfma_f32_16x16x32_bf16 v[96:99], v[210:213], v[174:177], v[96:99]
	v_mfma_f32_16x16x32_bf16 v[88:91], v[202:205], v[182:185], v[88:91]
	v_mfma_f32_16x16x32_bf16 v[80:83], v[210:213], v[182:185], v[80:83]
	v_mfma_f32_16x16x32_bf16 v[72:75], v[202:205], v[190:193], v[72:75]
	v_mfma_f32_16x16x32_bf16 v[64:67], v[210:213], v[190:193], v[64:67]
	v_mfma_f32_16x16x32_bf16 v[120:123], v[206:209], v[170:173], v[120:123]
	v_mfma_f32_16x16x32_bf16 v[112:115], v[214:217], v[170:173], v[112:115]
	v_mfma_f32_16x16x32_bf16 v[104:107], v[206:209], v[178:181], v[104:107]
	v_mfma_f32_16x16x32_bf16 v[96:99], v[214:217], v[178:181], v[96:99]
	v_mfma_f32_16x16x32_bf16 v[88:91], v[206:209], v[186:189], v[88:91]
	v_mfma_f32_16x16x32_bf16 v[80:83], v[214:217], v[186:189], v[80:83]
	v_mfma_f32_16x16x32_bf16 v[72:75], v[206:209], v[194:197], v[72:75]
	v_mfma_f32_16x16x32_bf16 v[64:67], v[214:217], v[194:197], v[64:67]
	s_setprio 0
	s_mov_b32 m0, s13
	v_lshl_add_u64 v[220:221], s[22:23], 0, v[134:135]
	s_barrier
	ds_read_b128 v[166:169], v148 offset:16384
	ds_read_b128 v[170:173], v148 offset:17408
	ds_read_b128 v[174:177], v148 offset:18432
	ds_read_b128 v[178:181], v148 offset:19456
	ds_read_b128 v[182:185], v148 offset:20480
	ds_read_b128 v[186:189], v148 offset:21504
	ds_read_b128 v[190:193], v148 offset:22528
	ds_read_b128 v[194:197], v148 offset:23552
	global_load_lds_dwordx4 v[220:221], off
	v_lshl_add_u64 v[222:223], s[22:23], 0, v[130:131]
	s_mov_b32 m0, s28
	s_nop 0
	global_load_lds_dwordx4 v[222:223], off
	s_barrier
	s_waitcnt lgkmcnt(0)
	s_setprio 1
	s_waitcnt lgkmcnt(0)
	v_mfma_f32_16x16x32_bf16 v[60:63], v[150:153], v[166:169], v[60:63]
	v_mfma_f32_16x16x32_bf16 v[56:59], v[158:161], v[166:169], v[56:59]
	v_mfma_f32_16x16x32_bf16 v[44:47], v[150:153], v[174:177], v[44:47]
	v_mfma_f32_16x16x32_bf16 v[40:43], v[158:161], v[174:177], v[40:43]
	v_mfma_f32_16x16x32_bf16 v[28:31], v[150:153], v[182:185], v[28:31]
	v_mfma_f32_16x16x32_bf16 v[24:27], v[158:161], v[182:185], v[24:27]
	v_mfma_f32_16x16x32_bf16 v[12:15], v[150:153], v[190:193], v[12:15]
	v_mfma_f32_16x16x32_bf16 v[8:11], v[158:161], v[190:193], v[8:11]
	v_mfma_f32_16x16x32_bf16 v[60:63], v[154:157], v[170:173], v[60:63]
	v_mfma_f32_16x16x32_bf16 v[56:59], v[162:165], v[170:173], v[56:59]
	v_mfma_f32_16x16x32_bf16 v[44:47], v[154:157], v[178:181], v[44:47]
	v_mfma_f32_16x16x32_bf16 v[40:43], v[162:165], v[178:181], v[40:43]
	v_mfma_f32_16x16x32_bf16 v[28:31], v[154:157], v[186:189], v[28:31]
	v_mfma_f32_16x16x32_bf16 v[24:27], v[162:165], v[186:189], v[24:27]
	v_mfma_f32_16x16x32_bf16 v[12:15], v[154:157], v[194:197], v[12:15]
	v_mfma_f32_16x16x32_bf16 v[8:11], v[162:165], v[194:197], v[8:11]
	s_setprio 0
	s_barrier
; #define PG8_STAGE(bufoff, gbase, voff) do { _Pragma("unroll") for (int _i = 0; _i < 2; ++_i) \
;         __builtin_amdgcn_global_load_lds((const unsigned*)((const char*)(gbase) + (voff)[_i]), (LAS unsigned*)(lds + (bufoff) + ldsw + _i * 8192), 16, 0, 0); } while (0)
; #define PG8_LDA(dst, b, h) do { _Pragma("unroll") for (int m = 0; m < 4; ++m) _Pragma("unroll") for (int k = 0; k < 2; ++k) dst[m][k] = *(const LAS bf16x8*)(lds + PG8_SA(b, h) + aoff + m * 2048 + k * 1024); } while (0)
; #define PG8_LDB(dst, b, h) do { _Pragma("unroll") for (int n = 0; n < 2; ++n) _Pragma("unroll") for (int k = 0; k < 2; ++k) dst[n][k] = *(const LAS bf16x8*)(lds + PG8_SB(b, h) + boff + n * 2048 + k * 1024); } while (0)
; #define PG8_MMA(ai, bj, At, Bt) do { __builtin_amdgcn_s_setprio(1); _Pragma("unroll") for (int m = 0; m < 4; ++m) _Pragma("unroll") for (int n = 0; n < 2; ++n) _Pragma("unroll") for (int k = 0; k < 2; ++k) \
;         acc[ai][bj][m][n] = __builtin_amdgcn_mfma_f32_16x16x32_bf16(Bt[n][k], At[m][k], acc[ai][bj][m][n], 0, 0, 0); __builtin_amdgcn_s_setprio(0); } while (0)
; #define PG8_WAIT_V(n) asm volatile("s_waitcnt vmcnt(" #n ")" ::: "memory")
; #define PG8_WAIT_L(n) asm volatile("s_waitcnt lgkmcnt(" #n ")" ::: "memory")
; #define PG8_BAR __builtin_amdgcn_s_barrier()
; #define PG8_SCHED __builtin_amdgcn_sched_barrier(0)
; template <class Epi, class Sched>
; __device__ __forceinline__ void gemm_phase(LAS unsigned char* lds, const Gemm g, const Sched& S, const Epi& E) {
;     ...
;             PG8_STAGE(PG8_SB(0, 1), b2 + hstep, voffB);
;             PG8_WAIT_V(6); PG8_BAR; PG8_MMA(1, 1, At, B1); PG8_BAR;
;             PG8_LDB(B0, 1, 0); PG8_SCHED; PG8_LDA(At, 1, 0); PG8_STAGE(PG8_SA(0, 1), a2 + hstep, voffA);
;             PG8_WAIT_L(8); PG8_BAR; PG8_WAIT_L(0); PG8_MMA(0, 0, At, B0); PG8_BAR; PG8_SCHED;
;             PG8_LDB(B1, 1, 1); PG8_STAGE(PG8_SB(1, 0), b3, voffB);
;             PG8_BAR; PG8_WAIT_L(0); PG8_MMA(0, 1, At, B1); PG8_BAR;
;             PG8_LDA(At, 1, 1); PG8_STAGE(PG8_SA(1, 0), a3, voffA);
	s_add_u32 s16, s18, 0x40000
	s_addc_u32 s17, s19, 0
	s_add_i32 s20, s41, s25
	v_lshl_add_u64 v[150:151], s[16:17], 0, v[132:133]
	s_mov_b32 m0, s20
	s_nop 0
	global_load_lds_dwordx4 v[150:151], off
	v_lshl_add_u64 v[150:151], s[16:17], 0, v[128:129]
	s_add_i32 m0, s20, 0x2000
	s_nop 0
	global_load_lds_dwordx4 v[150:151], off
	s_waitcnt vmcnt(6)
	s_barrier
	s_setprio 1
	v_mfma_f32_16x16x32_bf16 v[52:55], v[202:205], v[166:169], v[52:55]
	v_mfma_f32_16x16x32_bf16 v[48:51], v[210:213], v[166:169], v[48:51]
	v_mfma_f32_16x16x32_bf16 v[36:39], v[202:205], v[174:177], v[36:39]
	v_mfma_f32_16x16x32_bf16 v[32:35], v[210:213], v[174:177], v[32:35]
	v_mfma_f32_16x16x32_bf16 v[20:23], v[202:205], v[182:185], v[20:23]
	v_mfma_f32_16x16x32_bf16 v[16:19], v[210:213], v[182:185], v[16:19]
	v_mfma_f32_16x16x32_bf16 v[4:7], v[202:205], v[190:193], v[4:7]
	v_mfma_f32_16x16x32_bf16 v[0:3], v[210:213], v[190:193], v[0:3]
	v_mfma_f32_16x16x32_bf16 v[52:55], v[206:209], v[170:173], v[52:55]
	v_mfma_f32_16x16x32_bf16 v[48:51], v[214:217], v[170:173], v[48:51]
	v_mfma_f32_16x16x32_bf16 v[36:39], v[206:209], v[178:181], v[36:39]
	v_mfma_f32_16x16x32_bf16 v[32:35], v[214:217], v[178:181], v[32:35]
	v_mfma_f32_16x16x32_bf16 v[20:23], v[206:209], v[186:189], v[20:23]
	v_mfma_f32_16x16x32_bf16 v[16:19], v[214:217], v[186:189], v[16:19]
	v_mfma_f32_16x16x32_bf16 v[4:7], v[206:209], v[194:197], v[4:7]
	v_mfma_f32_16x16x32_bf16 v[0:3], v[214:217], v[194:197], v[0:3]
	s_setprio 0
	s_add_i32 s20, 0, 0x18000
	v_add_u32_e32 v162, s20, v146
	s_barrier
	ds_read_b128 v[150:153], v162
	ds_read_b128 v[154:157], v162 offset:1024
	ds_read_b128 v[158:161], v162 offset:2048
	ds_read_b128 v[162:165], v162 offset:3072
	s_add_u32 s16, s22, 0x40000
	s_addc_u32 s17, s23, 0
	s_mov_b32 m0, s29
	v_lshl_add_u64 v[202:203], s[16:17], 0, v[134:135]
	ds_read_b128 v[166:169], v148 offset:32768
	ds_read_b128 v[170:173], v148 offset:33792
	ds_read_b128 v[174:177], v148 offset:34816
	ds_read_b128 v[178:181], v148 offset:35840
	ds_read_b128 v[182:185], v148 offset:36864
	ds_read_b128 v[186:189], v148 offset:37888
	ds_read_b128 v[190:193], v148 offset:38912
	ds_read_b128 v[194:197], v148 offset:39936
	global_load_lds_dwordx4 v[202:203], off
	v_lshl_add_u64 v[202:203], s[16:17], 0, v[130:131]
	s_mov_b32 m0, s33
	s_nop 0
	global_load_lds_dwordx4 v[202:203], off
	s_waitcnt lgkmcnt(8)
	s_barrier
	s_waitcnt lgkmcnt(0)
	s_setprio 1
	s_waitcnt lgkmcnt(0)
	v_mfma_f32_16x16x32_bf16 v[124:127], v[150:153], v[166:169], v[124:127]
	v_mfma_f32_16x16x32_bf16 v[116:119], v[158:161], v[166:169], v[116:119]
	v_mfma_f32_16x16x32_bf16 v[108:111], v[150:153], v[174:177], v[108:111]
	v_mfma_f32_16x16x32_bf16 v[100:103], v[158:161], v[174:177], v[100:103]
	v_mfma_f32_16x16x32_bf16 v[92:95], v[150:153], v[182:185], v[92:95]
	v_mfma_f32_16x16x32_bf16 v[84:87], v[158:161], v[182:185], v[84:87]
	v_mfma_f32_16x16x32_bf16 v[76:79], v[150:153], v[190:193], v[76:79]
	v_mfma_f32_16x16x32_bf16 v[68:71], v[158:161], v[190:193], v[68:71]
	v_mfma_f32_16x16x32_bf16 v[124:127], v[154:157], v[170:173], v[124:127]
	v_mfma_f32_16x16x32_bf16 v[116:119], v[162:165], v[170:173], v[116:119]
	v_mfma_f32_16x16x32_bf16 v[108:111], v[154:157], v[178:181], v[108:111]
	v_mfma_f32_16x16x32_bf16 v[100:103], v[162:165], v[178:181], v[100:103]
	v_mfma_f32_16x16x32_bf16 v[92:95], v[154:157], v[186:189], v[92:95]
	v_mfma_f32_16x16x32_bf16 v[84:87], v[162:165], v[186:189], v[84:87]
	v_mfma_f32_16x16x32_bf16 v[76:79], v[154:157], v[194:197], v[76:79]
	v_mfma_f32_16x16x32_bf16 v[68:71], v[162:165], v[194:197], v[68:71]
	s_setprio 0
	s_barrier
	s_add_i32 s21, 0, 0x1c000
	s_add_i32 s16, s20, s25
	v_add_u32_e32 v214, s21, v146
	v_lshl_add_u64 v[198:199], v[198:199], 0, s[0:1]
	s_mov_b32 m0, s16
	ds_read_b128 v[202:205], v214
	ds_read_b128 v[206:209], v214 offset:1024
	ds_read_b128 v[210:213], v214 offset:2048
	ds_read_b128 v[214:217], v214 offset:3072
	global_load_lds_dwordx4 v[198:199], off
	v_lshl_add_u64 v[198:199], v[218:219], 0, s[0:1]
	s_add_i32 m0, s16, 0x2000
	s_nop 0
	global_load_lds_dwordx4 v[198:199], off
	s_barrier
	s_waitcnt lgkmcnt(0)
	s_setprio 1
	s_waitcnt lgkmcnt(0)
	v_mfma_f32_16x16x32_bf16 v[120:123], v[202:205], v[166:169], v[120:123]
	v_mfma_f32_16x16x32_bf16 v[112:115], v[210:213], v[166:169], v[112:115]
	v_mfma_f32_16x16x32_bf16 v[104:107], v[202:205], v[174:177], v[104:107]
	v_mfma_f32_16x16x32_bf16 v[96:99], v[210:213], v[174:177], v[96:99]
	v_mfma_f32_16x16x32_bf16 v[88:91], v[202:205], v[182:185], v[88:91]
	v_mfma_f32_16x16x32_bf16 v[80:83], v[210:213], v[182:185], v[80:83]
	v_mfma_f32_16x16x32_bf16 v[72:75], v[202:205], v[190:193], v[72:75]
	v_mfma_f32_16x16x32_bf16 v[64:67], v[210:213], v[190:193], v[64:67]
	v_mfma_f32_16x16x32_bf16 v[120:123], v[206:209], v[170:173], v[120:123]
	v_mfma_f32_16x16x32_bf16 v[112:115], v[214:217], v[170:173], v[112:115]
	v_mfma_f32_16x16x32_bf16 v[104:107], v[206:209], v[178:181], v[104:107]
	v_mfma_f32_16x16x32_bf16 v[96:99], v[214:217], v[178:181], v[96:99]
	v_mfma_f32_16x16x32_bf16 v[88:91], v[206:209], v[186:189], v[88:91]
	v_mfma_f32_16x16x32_bf16 v[80:83], v[214:217], v[186:189], v[80:83]
	v_mfma_f32_16x16x32_bf16 v[72:75], v[206:209], v[194:197], v[72:75]
	v_mfma_f32_16x16x32_bf16 v[64:67], v[214:217], v[194:197], v[64:67]
	s_setprio 0
	s_mov_b32 m0, s36
	v_lshl_add_u64 v[198:199], v[220:221], 0, s[0:1]
	s_barrier
	ds_read_b128 v[166:169], v148 offset:49152
	ds_read_b128 v[170:173], v148 offset:50176
	ds_read_b128 v[174:177], v148 offset:51200
	ds_read_b128 v[178:181], v148 offset:52224
	ds_read_b128 v[182:185], v148 offset:53248
	ds_read_b128 v[186:189], v148 offset:54272
	ds_read_b128 v[190:193], v148 offset:55296
	ds_read_b128 v[194:197], v148 offset:56320
	global_load_lds_dwordx4 v[198:199], off
	v_lshl_add_u64 v[198:199], v[222:223], 0, s[0:1]
	s_mov_b32 m0, s37
	s_nop 0
	global_load_lds_dwordx4 v[198:199], off
	s_barrier
; __device__ __forceinline__ unsigned cvt_pk_bf16(float lo, float hi) { unsigned r; asm volatile("v_cvt_pk_bf16_f32 %0, %1, %2" : "=v"(r) : "v"(lo), "v"(hi)); return r; }
; __device__ __forceinline__ float silu_f(float a) { return a * __builtin_amdgcn_rcpf(1.0f + __expf(-a)); }
; #define PG8_STAGE(bufoff, gbase, voff) do { _Pragma("unroll") for (int _i = 0; _i < 2; ++_i) \
;         __builtin_amdgcn_global_load_lds((const unsigned*)((const char*)(gbase) + (voff)[_i]), (LAS unsigned*)(lds + (bufoff) + ldsw + _i * 8192), 16, 0, 0); } while (0)
; #define PG8_MMA(ai, bj, At, Bt) do { __builtin_amdgcn_s_setprio(1); _Pragma("unroll") for (int m = 0; m < 4; ++m) _Pragma("unroll") for (int n = 0; n < 2; ++n) _Pragma("unroll") for (int k = 0; k < 2; ++k) \
;         acc[ai][bj][m][n] = __builtin_amdgcn_mfma_f32_16x16x32_bf16(Bt[n][k], At[m][k], acc[ai][bj][m][n], 0, 0, 0); __builtin_amdgcn_s_setprio(0); } while (0)
; #define PG8_WAIT_V(n) asm volatile("s_waitcnt vmcnt(" #n ")" ::: "memory")
; #define PG8_WAIT_L(n) asm volatile("s_waitcnt lgkmcnt(" #n ")" ::: "memory")
; template <class Epi, class Sched>
; __device__ __forceinline__ void gemm_phase(LAS unsigned char* lds, const Gemm g, const Sched& S, const Epi& E) {
;     ...
;             PG8_BAR; PG8_WAIT_L(0); PG8_MMA(1, 0, At, B0); PG8_BAR; PG8_SCHED;
;             PG8_STAGE(PG8_SB(1, 1), b3 + hstep, voffB);
;             PG8_WAIT_V(6); PG8_BAR; PG8_MMA(1, 1, At, B1); PG8_BAR;
;         }
;         E(acc, cur, wr, wc, fr, fq);
;     __device__ __forceinline__ void operator()(const AccT& acc, const Unit& u, int wr, int wc, int fr, int fq) const {
;         asm volatile("" : "+v"(fr), "+v"(fq));
;         const int row0 = u.pm * 256 + wr * 64 + fr, hc0 = u.pn * 128 + wc * 32 + 8 * fq;
; #pragma unroll
;         for (int ai = 0; ai < 2; ++ai)
; #pragma unroll
;             for (int m = 0; m < 4; ++m) {
;                 const f32x4 a0 = acc[ai][0][m][0], a1 = acc[ai][0][m][1], b0 = acc[ai][1][m][0], b1 = acc[ai][1][m][1];
;                 u32x4 w;
;                 w.x = cvt_pk_bf16(silu_f(a0[0]) * b0[0], silu_f(a0[1]) * b0[1]); w.y = cvt_pk_bf16(silu_f(a0[2]) * b0[2], silu_f(a0[3]) * b0[3]);
;                 w.z = cvt_pk_bf16(silu_f(a1[0]) * b1[0], silu_f(a1[1]) * b1[1]); w.w = cvt_pk_bf16(silu_f(a1[2]) * b1[2], silu_f(a1[3]) * b1[3]);
;                 *(u32x4*)(H + (size_t)(row0 + ai * 128 + m * 16) * DFF + hc0) = w;
	s_waitcnt lgkmcnt(0)
	s_setprio 1
	s_waitcnt lgkmcnt(0)
	v_mfma_f32_16x16x32_bf16 v[60:63], v[150:153], v[166:169], v[60:63]
	v_mfma_f32_16x16x32_bf16 v[56:59], v[158:161], v[166:169], v[56:59]
	v_mfma_f32_16x16x32_bf16 v[44:47], v[150:153], v[174:177], v[44:47]
	v_mfma_f32_16x16x32_bf16 v[40:43], v[158:161], v[174:177], v[40:43]
	v_mfma_f32_16x16x32_bf16 v[28:31], v[150:153], v[182:185], v[28:31]
	v_mfma_f32_16x16x32_bf16 v[24:27], v[158:161], v[182:185], v[24:27]
	v_mfma_f32_16x16x32_bf16 v[12:15], v[150:153], v[190:193], v[12:15]
	v_mfma_f32_16x16x32_bf16 v[8:11], v[158:161], v[190:193], v[8:11]
	v_mfma_f32_16x16x32_bf16 v[60:63], v[154:157], v[170:173], v[60:63]
	v_mfma_f32_16x16x32_bf16 v[56:59], v[162:165], v[170:173], v[56:59]
	v_mfma_f32_16x16x32_bf16 v[44:47], v[154:157], v[178:181], v[44:47]
	v_mfma_f32_16x16x32_bf16 v[40:43], v[162:165], v[178:181], v[40:43]
	v_mfma_f32_16x16x32_bf16 v[28:31], v[154:157], v[186:189], v[28:31]
	v_mfma_f32_16x16x32_bf16 v[24:27], v[162:165], v[186:189], v[24:27]
	v_mfma_f32_16x16x32_bf16 v[12:15], v[154:157], v[194:197], v[12:15]
	v_mfma_f32_16x16x32_bf16 v[8:11], v[162:165], v[194:197], v[8:11]
	s_setprio 0
	s_barrier
	s_add_u32 s16, s18, 0x40080
	s_addc_u32 s17, s19, 0
	s_add_i32 s18, s21, s25
	v_lshl_add_u64 v[150:151], s[16:17], 0, v[132:133]
	s_mov_b32 m0, s18
	s_nop 0
	global_load_lds_dwordx4 v[150:151], off
	v_lshl_add_u64 v[150:151], s[16:17], 0, v[128:129]
	s_add_i32 m0, s18, 0x2000
	s_nop 0
	global_load_lds_dwordx4 v[150:151], off
	s_waitcnt vmcnt(6)
	s_barrier
	s_setprio 1
	v_mfma_f32_16x16x32_bf16 v[52:55], v[202:205], v[166:169], v[52:55]
	v_mfma_f32_16x16x32_bf16 v[48:51], v[210:213], v[166:169], v[48:51]
	v_mfma_f32_16x16x32_bf16 v[36:39], v[202:205], v[174:177], v[36:39]
	v_mfma_f32_16x16x32_bf16 v[32:35], v[210:213], v[174:177], v[32:35]
	v_mfma_f32_16x16x32_bf16 v[20:23], v[202:205], v[182:185], v[20:23]
	v_mfma_f32_16x16x32_bf16 v[16:19], v[210:213], v[182:185], v[16:19]
	v_mfma_f32_16x16x32_bf16 v[4:7], v[202:205], v[190:193], v[4:7]
	v_mfma_f32_16x16x32_bf16 v[0:3], v[210:213], v[190:193], v[0:3]
	v_mfma_f32_16x16x32_bf16 v[52:55], v[206:209], v[170:173], v[52:55]
	v_mfma_f32_16x16x32_bf16 v[48:51], v[214:217], v[170:173], v[48:51]
	v_mfma_f32_16x16x32_bf16 v[36:39], v[206:209], v[178:181], v[36:39]
	v_mfma_f32_16x16x32_bf16 v[32:35], v[214:217], v[178:181], v[32:35]
	v_mfma_f32_16x16x32_bf16 v[20:23], v[206:209], v[186:189], v[20:23]
	v_mfma_f32_16x16x32_bf16 v[16:19], v[214:217], v[186:189], v[16:19]
	v_mfma_f32_16x16x32_bf16 v[4:7], v[206:209], v[194:197], v[4:7]
	v_mfma_f32_16x16x32_bf16 v[0:3], v[214:217], v[194:197], v[0:3]
	s_setprio 0
	s_add_i32 s48, s48, 2
	s_add_u32 s14, s14, 0x100
	s_addc_u32 s15, s15, 0
	s_add_u32 s46, s46, 0x100
	s_addc_u32 s47, s47, 0
	s_cmp_gt_u32 s48, 13
	s_barrier
	s_cbranch_scc0 .LBB0_235
	v_mov_b32_e32 v151, v145
	v_mov_b32_e32 v150, v144
	s_lshl_b32 s5, s12, 8
	s_add_i32 s5, s5, s34
	v_add_u32_e32 v150, s5, v150
	s_lshl_b32 s5, s43, 7
	s_or_b32 s5, s5, s35
	v_lshl_add_u32 v152, v151, 3, s5
	v_ashrrev_i32_e32 v153, 31, v152
	v_mov_b64_e32 v[154:155], s[82:83]
	v_lshlrev_b64 v[156:157], 1, v[152:153]
	v_mov_b32_e32 v158, 0xbfb8aa3b
	v_mov_b32_e32 v159, 0xbfb8aa3b
	v_mov_b32_e32 v160, 1.0
	v_mov_b32_e32 v161, 1.0
	v_pk_mul_f32 v[162:163], v[124:125], v[158:159]
	v_pk_mul_f32 v[164:165], v[126:127], v[158:159]
	v_pk_mul_f32 v[166:167], v[116:117], v[158:159]
	v_pk_mul_f32 v[168:169], v[118:119], v[158:159]
	v_pk_mul_f32 v[170:171], v[108:109], v[158:159]
	v_pk_mul_f32 v[172:173], v[110:111], v[158:159]
	v_pk_mul_f32 v[174:175], v[100:101], v[158:159]
	v_pk_mul_f32 v[176:177], v[102:103], v[158:159]
	v_exp_f32_e32 v162, v162
	v_exp_f32_e32 v163, v163
	v_exp_f32_e32 v164, v164
	v_exp_f32_e32 v165, v165
	v_exp_f32_e32 v166, v166
	v_exp_f32_e32 v167, v167
	v_exp_f32_e32 v168, v168
	v_exp_f32_e32 v169, v169
	v_exp_f32_e32 v170, v170
	v_exp_f32_e32 v171, v171
	v_exp_f32_e32 v172, v172
	v_exp_f32_e32 v173, v173
	v_exp_f32_e32 v174, v174
	v_exp_f32_e32 v175, v175
	v_exp_f32_e32 v176, v176
	v_exp_f32_e32 v177, v177
	v_pk_add_f32 v[162:163], v[162:163], v[160:161]
	v_pk_add_f32 v[164:165], v[164:165], v[160:161]
	v_pk_add_f32 v[166:167], v[166:167], v[160:161]
	v_pk_add_f32 v[168:169], v[168:169], v[160:161]
	v_pk_add_f32 v[170:171], v[170:171], v[160:161]
	v_pk_add_f32 v[172:173], v[172:173], v[160:161]
	v_pk_add_f32 v[174:175], v[174:175], v[160:161]
	v_pk_add_f32 v[176:177], v[176:177], v[160:161]
	v_rcp_f32_e32 v162, v162
	v_rcp_f32_e32 v163, v163
	v_rcp_f32_e32 v164, v164
	v_rcp_f32_e32 v165, v165
	v_rcp_f32_e32 v166, v166
	v_rcp_f32_e32 v167, v167
	v_rcp_f32_e32 v168, v168
	v_rcp_f32_e32 v169, v169
	v_rcp_f32_e32 v170, v170
	v_rcp_f32_e32 v171, v171
	v_rcp_f32_e32 v172, v172
	v_rcp_f32_e32 v173, v173
	v_rcp_f32_e32 v174, v174
	v_rcp_f32_e32 v175, v175
	v_rcp_f32_e32 v176, v176
	v_rcp_f32_e32 v177, v177
	v_mad_i64_i32 v[178:179], s[14:15], v150, s42, v[154:155]
	v_lshl_add_u64 v[178:179], v[178:179], 0, v[156:157]
	v_add_u32_e32 v195, 0x10, v150
	v_mad_i64_i32 v[180:181], s[14:15], v195, s42, v[154:155]
	v_lshl_add_u64 v[180:181], v[180:181], 0, v[156:157]
	v_pk_mul_f32 v[124:125], v[124:125], v[162:163]
	v_pk_mul_f32 v[126:127], v[126:127], v[164:165]
	v_pk_mul_f32 v[116:117], v[116:117], v[166:167]
	v_pk_mul_f32 v[118:119], v[118:119], v[168:169]
	v_pk_mul_f32 v[108:109], v[108:109], v[170:171]
	v_pk_mul_f32 v[110:111], v[110:111], v[172:173]
	v_pk_mul_f32 v[100:101], v[100:101], v[174:175]
	v_pk_mul_f32 v[102:103], v[102:103], v[176:177]
	v_pk_mul_f32 v[124:125], v[124:125], v[120:121]
	v_pk_mul_f32 v[126:127], v[126:127], v[122:123]
; __device__ __forceinline__ unsigned cvt_pk_bf16(float lo, float hi) { unsigned r; asm volatile("v_cvt_pk_bf16_f32 %0, %1, %2" : "=v"(r) : "v"(lo), "v"(hi)); return r; }
; __device__ __forceinline__ float silu_f(float a) { return a * __builtin_amdgcn_rcpf(1.0f + __expf(-a)); }
;     __device__ __forceinline__ void operator()(const AccT& acc, const Unit& u, int wr, int wc, int fr, int fq) const {
;     ...
;                 const f32x4 a0 = acc[ai][0][m][0], a1 = acc[ai][0][m][1], b0 = acc[ai][1][m][0], b1 = acc[ai][1][m][1];
;                 u32x4 w;
;                 w.x = cvt_pk_bf16(silu_f(a0[0]) * b0[0], silu_f(a0[1]) * b0[1]); w.y = cvt_pk_bf16(silu_f(a0[2]) * b0[2], silu_f(a0[3]) * b0[3]);
;                 w.z = cvt_pk_bf16(silu_f(a1[0]) * b1[0], silu_f(a1[1]) * b1[1]); w.w = cvt_pk_bf16(silu_f(a1[2]) * b1[2], silu_f(a1[3]) * b1[3]);
;                 *(u32x4*)(H + (size_t)(row0 + ai * 128 + m * 16) * DFF + hc0) = w;
	v_pk_mul_f32 v[116:117], v[116:117], v[112:113]
	v_pk_mul_f32 v[118:119], v[118:119], v[114:115]
	v_pk_mul_f32 v[108:109], v[108:109], v[104:105]
	v_pk_mul_f32 v[110:111], v[110:111], v[106:107]
	v_pk_mul_f32 v[100:101], v[100:101], v[96:97]
	v_pk_mul_f32 v[102:103], v[102:103], v[98:99]
	v_cvt_pk_bf16_f32 v120, v124, v125
	v_cvt_pk_bf16_f32 v121, v126, v127
	v_cvt_pk_bf16_f32 v122, v116, v117
	v_cvt_pk_bf16_f32 v123, v118, v119
	global_store_dwordx4 v[178:179], v[120:123], off
	v_cvt_pk_bf16_f32 v104, v108, v109
	v_cvt_pk_bf16_f32 v105, v110, v111
	v_cvt_pk_bf16_f32 v106, v100, v101
	v_cvt_pk_bf16_f32 v107, v102, v103
	global_store_dwordx4 v[180:181], v[104:107], off
	v_pk_mul_f32 v[162:163], v[92:93], v[158:159]
	v_pk_mul_f32 v[164:165], v[94:95], v[158:159]
	v_pk_mul_f32 v[166:167], v[84:85], v[158:159]
	v_pk_mul_f32 v[168:169], v[86:87], v[158:159]
	v_pk_mul_f32 v[170:171], v[76:77], v[158:159]
	v_pk_mul_f32 v[172:173], v[78:79], v[158:159]
	v_pk_mul_f32 v[174:175], v[68:69], v[158:159]
	v_pk_mul_f32 v[176:177], v[70:71], v[158:159]
	v_exp_f32_e32 v162, v162
	v_exp_f32_e32 v163, v163
	v_exp_f32_e32 v164, v164
	v_exp_f32_e32 v165, v165
	v_exp_f32_e32 v166, v166
	v_exp_f32_e32 v167, v167
	v_exp_f32_e32 v168, v168
	v_exp_f32_e32 v169, v169
	v_exp_f32_e32 v170, v170
	v_exp_f32_e32 v171, v171
	v_exp_f32_e32 v172, v172
	v_exp_f32_e32 v173, v173
	v_exp_f32_e32 v174, v174
	v_exp_f32_e32 v175, v175
	v_exp_f32_e32 v176, v176
	v_exp_f32_e32 v177, v177
	v_pk_add_f32 v[162:163], v[162:163], v[160:161]
	v_pk_add_f32 v[164:165], v[164:165], v[160:161]
	v_pk_add_f32 v[166:167], v[166:167], v[160:161]
	v_pk_add_f32 v[168:169], v[168:169], v[160:161]
	v_pk_add_f32 v[170:171], v[170:171], v[160:161]
	v_pk_add_f32 v[172:173], v[172:173], v[160:161]
	v_pk_add_f32 v[174:175], v[174:175], v[160:161]
	v_pk_add_f32 v[176:177], v[176:177], v[160:161]
	v_rcp_f32_e32 v162, v162
	v_rcp_f32_e32 v163, v163
	v_rcp_f32_e32 v164, v164
	v_rcp_f32_e32 v165, v165
	v_rcp_f32_e32 v166, v166
	v_rcp_f32_e32 v167, v167
	v_rcp_f32_e32 v168, v168
	v_rcp_f32_e32 v169, v169
	v_rcp_f32_e32 v170, v170
	v_rcp_f32_e32 v171, v171
	v_rcp_f32_e32 v172, v172
	v_rcp_f32_e32 v173, v173
	v_rcp_f32_e32 v174, v174
	v_rcp_f32_e32 v175, v175
	v_rcp_f32_e32 v176, v176
	v_rcp_f32_e32 v177, v177
	v_add_u32_e32 v196, 0x20, v150
	v_mad_i64_i32 v[182:183], s[14:15], v196, s42, v[154:155]
	v_lshl_add_u64 v[182:183], v[182:183], 0, v[156:157]
	v_add_u32_e32 v197, 0x30, v150
	v_mad_i64_i32 v[184:185], s[14:15], v197, s42, v[154:155]
	v_lshl_add_u64 v[184:185], v[184:185], 0, v[156:157]
	v_pk_mul_f32 v[92:93], v[92:93], v[162:163]
	v_pk_mul_f32 v[94:95], v[94:95], v[164:165]
	v_pk_mul_f32 v[84:85], v[84:85], v[166:167]
	v_pk_mul_f32 v[86:87], v[86:87], v[168:169]
	v_pk_mul_f32 v[76:77], v[76:77], v[170:171]
	v_pk_mul_f32 v[78:79], v[78:79], v[172:173]
	v_pk_mul_f32 v[68:69], v[68:69], v[174:175]
	v_pk_mul_f32 v[70:71], v[70:71], v[176:177]
	v_pk_mul_f32 v[92:93], v[92:93], v[88:89]
	v_pk_mul_f32 v[94:95], v[94:95], v[90:91]
	v_pk_mul_f32 v[84:85], v[84:85], v[80:81]
	v_pk_mul_f32 v[86:87], v[86:87], v[82:83]
	v_pk_mul_f32 v[76:77], v[76:77], v[72:73]
	v_pk_mul_f32 v[78:79], v[78:79], v[74:75]
	v_pk_mul_f32 v[68:69], v[68:69], v[64:65]
	v_pk_mul_f32 v[70:71], v[70:71], v[66:67]
	v_cvt_pk_bf16_f32 v88, v92, v93
	v_cvt_pk_bf16_f32 v89, v94, v95
	v_cvt_pk_bf16_f32 v90, v84, v85
	v_cvt_pk_bf16_f32 v91, v86, v87
	global_store_dwordx4 v[182:183], v[88:91], off
	v_cvt_pk_bf16_f32 v72, v76, v77
	v_cvt_pk_bf16_f32 v73, v78, v79
	v_cvt_pk_bf16_f32 v74, v68, v69
	v_cvt_pk_bf16_f32 v75, v70, v71
	global_store_dwordx4 v[184:185], v[72:75], off
	v_pk_mul_f32 v[162:163], v[60:61], v[158:159]
	v_pk_mul_f32 v[164:165], v[62:63], v[158:159]
	v_pk_mul_f32 v[166:167], v[56:57], v[158:159]
	v_pk_mul_f32 v[168:169], v[58:59], v[158:159]
	v_pk_mul_f32 v[170:171], v[44:45], v[158:159]
	v_pk_mul_f32 v[172:173], v[46:47], v[158:159]
	v_pk_mul_f32 v[174:175], v[40:41], v[158:159]
	v_pk_mul_f32 v[176:177], v[42:43], v[158:159]
	v_exp_f32_e32 v162, v162
	v_exp_f32_e32 v163, v163
	v_exp_f32_e32 v164, v164
	v_exp_f32_e32 v165, v165
	v_exp_f32_e32 v166, v166
	v_exp_f32_e32 v167, v167
	v_exp_f32_e32 v168, v168
	v_exp_f32_e32 v169, v169
	v_exp_f32_e32 v170, v170
	v_exp_f32_e32 v171, v171
	v_exp_f32_e32 v172, v172
	v_exp_f32_e32 v173, v173
	v_exp_f32_e32 v174, v174
	v_exp_f32_e32 v175, v175
	v_exp_f32_e32 v176, v176
	v_exp_f32_e32 v177, v177
	v_pk_add_f32 v[162:163], v[162:163], v[160:161]
	v_pk_add_f32 v[164:165], v[164:165], v[160:161]
	v_pk_add_f32 v[166:167], v[166:167], v[160:161]
	v_pk_add_f32 v[168:169], v[168:169], v[160:161]
	v_pk_add_f32 v[170:171], v[170:171], v[160:161]
	v_pk_add_f32 v[172:173], v[172:173], v[160:161]
	v_pk_add_f32 v[174:175], v[174:175], v[160:161]
	v_pk_add_f32 v[176:177], v[176:177], v[160:161]
	v_rcp_f32_e32 v162, v162
	v_rcp_f32_e32 v163, v163
; __device__ __forceinline__ unsigned cvt_pk_bf16(float lo, float hi) { unsigned r; asm volatile("v_cvt_pk_bf16_f32 %0, %1, %2" : "=v"(r) : "v"(lo), "v"(hi)); return r; }
; __device__ __forceinline__ float silu_f(float a) { return a * __builtin_amdgcn_rcpf(1.0f + __expf(-a)); }
; #define PG8_WAIT_V(n) asm volatile("s_waitcnt vmcnt(" #n ")" ::: "memory")
; #define PG8_BAR __builtin_amdgcn_s_barrier()
; template <class Epi, class Sched>
; __device__ __forceinline__ void gemm_phase(LAS unsigned char* lds, const Gemm g, const Sched& S, const Epi& E) {
;     ...
;         if (!has_next) break;
; #pragma unroll
;         for (int a = 0; a < 2; ++a)
; #pragma unroll
;             for (int b = 0; b < 2; ++b)
; #pragma unroll
;                 for (int m = 0; m < 4; ++m)
; #pragma unroll
;                     for (int n = 0; n < 2; ++n) acc[a][b][m][n] = (f32x4){0.f, 0.f, 0.f, 0.f};
;         cur = nxt; cA = nA; cB = nB; ++ui;
;     }
;     PG8_WAIT_V(0);
;     if (wr == 0) PG8_BAR;
;     PG8_BAR;
;     __device__ __forceinline__ void operator()(const AccT& acc, const Unit& u, int wr, int wc, int fr, int fq) const {
;     ...
;                 const f32x4 a0 = acc[ai][0][m][0], a1 = acc[ai][0][m][1], b0 = acc[ai][1][m][0], b1 = acc[ai][1][m][1];
;                 u32x4 w;
;                 w.x = cvt_pk_bf16(silu_f(a0[0]) * b0[0], silu_f(a0[1]) * b0[1]); w.y = cvt_pk_bf16(silu_f(a0[2]) * b0[2], silu_f(a0[3]) * b0[3]);
;                 w.z = cvt_pk_bf16(silu_f(a1[0]) * b1[0], silu_f(a1[1]) * b1[1]); w.w = cvt_pk_bf16(silu_f(a1[2]) * b1[2], silu_f(a1[3]) * b1[3]);
;                 *(u32x4*)(H + (size_t)(row0 + ai * 128 + m * 16) * DFF + hc0) = w;
	v_rcp_f32_e32 v164, v164
	v_rcp_f32_e32 v165, v165
	v_rcp_f32_e32 v166, v166
	v_rcp_f32_e32 v167, v167
	v_rcp_f32_e32 v168, v168
	v_rcp_f32_e32 v169, v169
	v_rcp_f32_e32 v170, v170
	v_rcp_f32_e32 v171, v171
	v_rcp_f32_e32 v172, v172
	v_rcp_f32_e32 v173, v173
	v_rcp_f32_e32 v174, v174
	v_rcp_f32_e32 v175, v175
	v_rcp_f32_e32 v176, v176
	v_rcp_f32_e32 v177, v177
	v_add_u32_e32 v198, 0x80, v150
	v_mad_i64_i32 v[186:187], s[14:15], v198, s42, v[154:155]
	v_lshl_add_u64 v[186:187], v[186:187], 0, v[156:157]
	v_add_u32_e32 v199, 0x90, v150
	v_mad_i64_i32 v[188:189], s[14:15], v199, s42, v[154:155]
	v_lshl_add_u64 v[188:189], v[188:189], 0, v[156:157]
	v_pk_mul_f32 v[60:61], v[60:61], v[162:163]
	v_pk_mul_f32 v[62:63], v[62:63], v[164:165]
	v_pk_mul_f32 v[56:57], v[56:57], v[166:167]
	v_pk_mul_f32 v[58:59], v[58:59], v[168:169]
	v_pk_mul_f32 v[44:45], v[44:45], v[170:171]
	v_pk_mul_f32 v[46:47], v[46:47], v[172:173]
	v_pk_mul_f32 v[40:41], v[40:41], v[174:175]
	v_pk_mul_f32 v[42:43], v[42:43], v[176:177]
	v_pk_mul_f32 v[60:61], v[60:61], v[52:53]
	v_pk_mul_f32 v[62:63], v[62:63], v[54:55]
	v_pk_mul_f32 v[56:57], v[56:57], v[48:49]
	v_pk_mul_f32 v[58:59], v[58:59], v[50:51]
	v_pk_mul_f32 v[44:45], v[44:45], v[36:37]
	v_pk_mul_f32 v[46:47], v[46:47], v[38:39]
	v_pk_mul_f32 v[40:41], v[40:41], v[32:33]
	v_pk_mul_f32 v[42:43], v[42:43], v[34:35]
	v_cvt_pk_bf16_f32 v52, v60, v61
	v_cvt_pk_bf16_f32 v53, v62, v63
	v_cvt_pk_bf16_f32 v54, v56, v57
	v_cvt_pk_bf16_f32 v55, v58, v59
	global_store_dwordx4 v[186:187], v[52:55], off
	v_cvt_pk_bf16_f32 v36, v44, v45
	v_cvt_pk_bf16_f32 v37, v46, v47
	v_cvt_pk_bf16_f32 v38, v40, v41
	v_cvt_pk_bf16_f32 v39, v42, v43
	global_store_dwordx4 v[188:189], v[36:39], off
	v_pk_mul_f32 v[162:163], v[28:29], v[158:159]
	v_pk_mul_f32 v[164:165], v[30:31], v[158:159]
	v_pk_mul_f32 v[166:167], v[24:25], v[158:159]
	v_pk_mul_f32 v[168:169], v[26:27], v[158:159]
	v_pk_mul_f32 v[170:171], v[12:13], v[158:159]
	v_pk_mul_f32 v[172:173], v[14:15], v[158:159]
	v_pk_mul_f32 v[174:175], v[8:9], v[158:159]
	v_pk_mul_f32 v[176:177], v[10:11], v[158:159]
	v_exp_f32_e32 v162, v162
	v_exp_f32_e32 v163, v163
	v_exp_f32_e32 v164, v164
	v_exp_f32_e32 v165, v165
	v_exp_f32_e32 v166, v166
	v_exp_f32_e32 v167, v167
	v_exp_f32_e32 v168, v168
	v_exp_f32_e32 v169, v169
	v_exp_f32_e32 v170, v170
	v_exp_f32_e32 v171, v171
	v_exp_f32_e32 v172, v172
	v_exp_f32_e32 v173, v173
	v_exp_f32_e32 v174, v174
	v_exp_f32_e32 v175, v175
	v_exp_f32_e32 v176, v176
	v_exp_f32_e32 v177, v177
	v_pk_add_f32 v[162:163], v[162:163], v[160:161]
	v_pk_add_f32 v[164:165], v[164:165], v[160:161]
	v_pk_add_f32 v[166:167], v[166:167], v[160:161]
	v_pk_add_f32 v[168:169], v[168:169], v[160:161]
	v_pk_add_f32 v[170:171], v[170:171], v[160:161]
	v_pk_add_f32 v[172:173], v[172:173], v[160:161]
	v_pk_add_f32 v[174:175], v[174:175], v[160:161]
	v_pk_add_f32 v[176:177], v[176:177], v[160:161]
	v_rcp_f32_e32 v162, v162
	v_rcp_f32_e32 v163, v163
	v_rcp_f32_e32 v164, v164
	v_rcp_f32_e32 v165, v165
	v_rcp_f32_e32 v166, v166
	v_rcp_f32_e32 v167, v167
	v_rcp_f32_e32 v168, v168
	v_rcp_f32_e32 v169, v169
	v_rcp_f32_e32 v170, v170
	v_rcp_f32_e32 v171, v171
	v_rcp_f32_e32 v172, v172
	v_rcp_f32_e32 v173, v173
	v_rcp_f32_e32 v174, v174
	v_rcp_f32_e32 v175, v175
	v_rcp_f32_e32 v176, v176
	v_rcp_f32_e32 v177, v177
	v_add_u32_e32 v202, 0xa0, v150
	v_mad_i64_i32 v[190:191], s[14:15], v202, s42, v[154:155]
	v_lshl_add_u64 v[190:191], v[190:191], 0, v[156:157]
	v_add_u32_e32 v203, 0xb0, v150
	v_mad_i64_i32 v[192:193], s[14:15], v203, s42, v[154:155]
	v_lshl_add_u64 v[192:193], v[192:193], 0, v[156:157]
	v_pk_mul_f32 v[28:29], v[28:29], v[162:163]
	v_pk_mul_f32 v[30:31], v[30:31], v[164:165]
	v_pk_mul_f32 v[24:25], v[24:25], v[166:167]
	v_pk_mul_f32 v[26:27], v[26:27], v[168:169]
	v_pk_mul_f32 v[12:13], v[12:13], v[170:171]
	v_pk_mul_f32 v[14:15], v[14:15], v[172:173]
	v_pk_mul_f32 v[8:9], v[8:9], v[174:175]
	v_pk_mul_f32 v[10:11], v[10:11], v[176:177]
	v_pk_mul_f32 v[28:29], v[28:29], v[20:21]
	v_pk_mul_f32 v[30:31], v[30:31], v[22:23]
	v_pk_mul_f32 v[24:25], v[24:25], v[16:17]
	v_pk_mul_f32 v[26:27], v[26:27], v[18:19]
	v_pk_mul_f32 v[12:13], v[12:13], v[4:5]
	v_pk_mul_f32 v[14:15], v[14:15], v[6:7]
	v_pk_mul_f32 v[8:9], v[8:9], v[0:1]
	v_pk_mul_f32 v[10:11], v[10:11], v[2:3]
	v_cvt_pk_bf16_f32 v20, v28, v29
	v_cvt_pk_bf16_f32 v21, v30, v31
	v_cvt_pk_bf16_f32 v22, v24, v25
	v_cvt_pk_bf16_f32 v23, v26, v27
	global_store_dwordx4 v[190:191], v[20:23], off
	v_cvt_pk_bf16_f32 v4, v12, v13
	v_cvt_pk_bf16_f32 v5, v14, v15
	v_cvt_pk_bf16_f32 v6, v8, v9
	v_cvt_pk_bf16_f32 v7, v10, v11
	s_and_b64 vcc, exec, s[2:3]
	s_mov_b32 s43, s4
	s_mov_b32 s12, s6
	s_mov_b64 s[18:19], s[10:11]
	s_mov_b64 s[14:15], s[8:9]
	global_store_dwordx4 v[192:193], v[4:7], off
	s_cbranch_vccz .LBB0_232
	s_waitcnt vmcnt(0)
	s_cmpk_gt_u32 s24, 0xff
	s_cbranch_scc1 .LBB0_239
	s_barrier

; #define PG8_STAGE(bufoff, gbase, voff) do { _Pragma("unroll") for (int _i = 0; _i < 2; ++_i) \
;         __builtin_amdgcn_global_load_lds((const unsigned*)((const char*)(gbase) + (voff)[_i]), (LAS unsigned*)(lds + (bufoff) + ldsw + _i * 8192), 16, 0, 0); } while (0)
; #define PG8_LDA(dst, b, h) do { _Pragma("unroll") for (int m = 0; m < 4; ++m) _Pragma("unroll") for (int k = 0; k < 2; ++k) dst[m][k] = *(const LAS bf16x8*)(lds + PG8_SA(b, h) + aoff + m * 2048 + k * 1024); } while (0)
; #define PG8_LDB(dst, b, h) do { _Pragma("unroll") for (int n = 0; n < 2; ++n) _Pragma("unroll") for (int k = 0; k < 2; ++k) dst[n][k] = *(const LAS bf16x8*)(lds + PG8_SB(b, h) + boff + n * 2048 + k * 1024); } while (0)
; #define PG8_MMA(ai, bj, At, Bt) do { __builtin_amdgcn_s_setprio(1); _Pragma("unroll") for (int m = 0; m < 4; ++m) _Pragma("unroll") for (int n = 0; n < 2; ++n) _Pragma("unroll") for (int k = 0; k < 2; ++k) \
;         acc[ai][bj][m][n] = __builtin_amdgcn_mfma_f32_16x16x32_bf16(Bt[n][k], At[m][k], acc[ai][bj][m][n], 0, 0, 0); __builtin_amdgcn_s_setprio(0); } while (0)
; #define PG8_WAIT_L(n) asm volatile("s_waitcnt lgkmcnt(" #n ")" ::: "memory")
; #define PG8_BAR __builtin_amdgcn_s_barrier()
; #define PG8_SCHED __builtin_amdgcn_sched_barrier(0)
; template <class Epi, class Sched>
; __device__ __forceinline__ void gemm_phase(LAS unsigned char* lds, const Gemm g, const Sched& S, const Epi& E) {
;     ...
;             PG8_LDB(B0, 0, 0); PG8_SCHED; PG8_LDA(At, 0, 0); PG8_STAGE(PG8_SA(1, 1), a1 + hstep, voffA);
;             PG8_WAIT_L(8); PG8_BAR; PG8_WAIT_L(0); PG8_MMA(0, 0, At, B0); PG8_BAR; PG8_SCHED;
;             PG8_LDB(B1, 0, 1); PG8_STAGE(PG8_SB(0, 0), b2, voffB);
;             PG8_BAR; PG8_WAIT_L(0); PG8_MMA(0, 1, At, B1); PG8_BAR;
;             PG8_LDA(At, 0, 1); PG8_STAGE(PG8_SA(0, 0), a2, voffA);
;             PG8_BAR; PG8_WAIT_L(0); PG8_MMA(1, 0, At, B0); PG8_BAR; PG8_SCHED;
.LBB0_1021:
	ds_read_b128 v[150:153], v147
	ds_read_b128 v[154:157], v147 offset:1024
	ds_read_b128 v[158:161], v147 offset:2048
	ds_read_b128 v[162:165], v147 offset:3072
	s_add_u32 s18, s16, 0xfffc0080
	s_addc_u32 s19, s17, -1
	s_cmp_eq_u32 s46, 12
	s_cselect_b32 s21, s7, s19
	s_cselect_b32 s20, s42, s18
	s_cselect_b32 s19, s5, s45
	s_cselect_b32 s18, s43, s44
	v_lshl_add_u64 v[198:199], s[16:17], 0, v[136:137]
	s_add_i32 m0, s15, 0xc000
	ds_read_b128 v[166:169], v148
	ds_read_b128 v[170:173], v148 offset:1024
	ds_read_b128 v[174:177], v148 offset:2048
	ds_read_b128 v[178:181], v148 offset:3072
	ds_read_b128 v[182:185], v148 offset:4096
	ds_read_b128 v[186:189], v148 offset:5120
	ds_read_b128 v[190:193], v148 offset:6144
	ds_read_b128 v[194:197], v148 offset:7168
	global_load_lds_dwordx4 v[198:199], off
	v_lshl_add_u64 v[198:199], s[16:17], 0, v[138:139]
	s_add_i32 m0, s15, 0xe000
	s_nop 0
	global_load_lds_dwordx4 v[198:199], off
	s_waitcnt lgkmcnt(8)
	s_barrier
	s_waitcnt lgkmcnt(0)
	s_setprio 1
	s_waitcnt lgkmcnt(0)
	v_mfma_f32_16x16x32_bf16 v[124:127], v[150:153], v[166:169], v[124:127]
	v_mfma_f32_16x16x32_bf16 v[116:119], v[158:161], v[166:169], v[116:119]
	v_mfma_f32_16x16x32_bf16 v[108:111], v[150:153], v[174:177], v[108:111]
	v_mfma_f32_16x16x32_bf16 v[100:103], v[158:161], v[174:177], v[100:103]
	v_mfma_f32_16x16x32_bf16 v[92:95], v[150:153], v[182:185], v[92:95]
	v_mfma_f32_16x16x32_bf16 v[84:87], v[158:161], v[182:185], v[84:87]
	v_mfma_f32_16x16x32_bf16 v[76:79], v[150:153], v[190:193], v[76:79]
	v_mfma_f32_16x16x32_bf16 v[68:71], v[158:161], v[190:193], v[68:71]
	v_mfma_f32_16x16x32_bf16 v[124:127], v[154:157], v[170:173], v[124:127]
	v_mfma_f32_16x16x32_bf16 v[116:119], v[162:165], v[170:173], v[116:119]
	v_mfma_f32_16x16x32_bf16 v[108:111], v[154:157], v[178:181], v[108:111]
	v_mfma_f32_16x16x32_bf16 v[100:103], v[162:165], v[178:181], v[100:103]
	v_mfma_f32_16x16x32_bf16 v[92:95], v[154:157], v[186:189], v[92:95]
	v_mfma_f32_16x16x32_bf16 v[84:87], v[162:165], v[186:189], v[84:87]
	v_mfma_f32_16x16x32_bf16 v[76:79], v[154:157], v[194:197], v[76:79]
	v_mfma_f32_16x16x32_bf16 v[68:71], v[162:165], v[194:197], v[68:71]
	s_setprio 0
	s_barrier
	s_add_i32 s47, s38, s25
	v_lshl_add_u64 v[198:199], s[18:19], 0, v[132:133]
	s_mov_b32 m0, s47
	ds_read_b128 v[202:205], v149
	ds_read_b128 v[206:209], v149 offset:1024
	ds_read_b128 v[210:213], v149 offset:2048
	ds_read_b128 v[214:217], v149 offset:3072
	global_load_lds_dwordx4 v[198:199], off
	v_lshl_add_u64 v[218:219], s[18:19], 0, v[128:129]
	s_add_i32 m0, s47, 0x2000
	s_nop 0
	global_load_lds_dwordx4 v[218:219], off
	s_barrier
	s_waitcnt lgkmcnt(0)
	s_setprio 1
	s_waitcnt lgkmcnt(0)
	v_mfma_f32_16x16x32_bf16 v[120:123], v[202:205], v[166:169], v[120:123]
	v_mfma_f32_16x16x32_bf16 v[112:115], v[210:213], v[166:169], v[112:115]
	v_mfma_f32_16x16x32_bf16 v[104:107], v[202:205], v[174:177], v[104:107]
	v_mfma_f32_16x16x32_bf16 v[96:99], v[210:213], v[174:177], v[96:99]
	v_mfma_f32_16x16x32_bf16 v[88:91], v[202:205], v[182:185], v[88:91]
	v_mfma_f32_16x16x32_bf16 v[80:83], v[210:213], v[182:185], v[80:83]
	v_mfma_f32_16x16x32_bf16 v[72:75], v[202:205], v[190:193], v[72:75]
	v_mfma_f32_16x16x32_bf16 v[64:67], v[210:213], v[190:193], v[64:67]
	v_mfma_f32_16x16x32_bf16 v[120:123], v[206:209], v[170:173], v[120:123]
	v_mfma_f32_16x16x32_bf16 v[112:115], v[214:217], v[170:173], v[112:115]
	v_mfma_f32_16x16x32_bf16 v[104:107], v[206:209], v[178:181], v[104:107]
	v_mfma_f32_16x16x32_bf16 v[96:99], v[214:217], v[178:181], v[96:99]
	v_mfma_f32_16x16x32_bf16 v[88:91], v[206:209], v[186:189], v[88:91]
	v_mfma_f32_16x16x32_bf16 v[80:83], v[214:217], v[186:189], v[80:83]
	v_mfma_f32_16x16x32_bf16 v[72:75], v[206:209], v[194:197], v[72:75]
	v_mfma_f32_16x16x32_bf16 v[64:67], v[214:217], v[194:197], v[64:67]
	s_setprio 0
	s_mov_b32 m0, s15
	v_lshl_add_u64 v[220:221], s[20:21], 0, v[134:135]
	s_barrier
	ds_read_b128 v[166:169], v148 offset:16384
	ds_read_b128 v[170:173], v148 offset:17408
	ds_read_b128 v[174:177], v148 offset:18432
	ds_read_b128 v[178:181], v148 offset:19456
	ds_read_b128 v[182:185], v148 offset:20480
	ds_read_b128 v[186:189], v148 offset:21504
	ds_read_b128 v[190:193], v148 offset:22528
	ds_read_b128 v[194:197], v148 offset:23552
	global_load_lds_dwordx4 v[220:221], off
	v_lshl_add_u64 v[222:223], s[20:21], 0, v[130:131]
	s_mov_b32 m0, s28
	s_nop 0
	global_load_lds_dwordx4 v[222:223], off
	s_barrier
	s_waitcnt lgkmcnt(0)
	s_setprio 1
	s_waitcnt lgkmcnt(0)
	v_mfma_f32_16x16x32_bf16 v[60:63], v[150:153], v[166:169], v[60:63]
	v_mfma_f32_16x16x32_bf16 v[56:59], v[158:161], v[166:169], v[56:59]
	v_mfma_f32_16x16x32_bf16 v[44:47], v[150:153], v[174:177], v[44:47]
	v_mfma_f32_16x16x32_bf16 v[40:43], v[158:161], v[174:177], v[40:43]
	v_mfma_f32_16x16x32_bf16 v[28:31], v[150:153], v[182:185], v[28:31]
	v_mfma_f32_16x16x32_bf16 v[24:27], v[158:161], v[182:185], v[24:27]
	v_mfma_f32_16x16x32_bf16 v[12:15], v[150:153], v[190:193], v[12:15]
	v_mfma_f32_16x16x32_bf16 v[8:11], v[158:161], v[190:193], v[8:11]
	v_mfma_f32_16x16x32_bf16 v[60:63], v[154:157], v[170:173], v[60:63]
	v_mfma_f32_16x16x32_bf16 v[56:59], v[162:165], v[170:173], v[56:59]
	v_mfma_f32_16x16x32_bf16 v[44:47], v[154:157], v[178:181], v[44:47]
	v_mfma_f32_16x16x32_bf16 v[40:43], v[162:165], v[178:181], v[40:43]
	v_mfma_f32_16x16x32_bf16 v[28:31], v[154:157], v[186:189], v[28:31]
	v_mfma_f32_16x16x32_bf16 v[24:27], v[162:165], v[186:189], v[24:27]
	v_mfma_f32_16x16x32_bf16 v[12:15], v[154:157], v[194:197], v[12:15]
	v_mfma_f32_16x16x32_bf16 v[8:11], v[162:165], v[194:197], v[8:11]
	s_setprio 0
	s_barrier
; #define PG8_STAGE(bufoff, gbase, voff) do { _Pragma("unroll") for (int _i = 0; _i < 2; ++_i) \
;         __builtin_amdgcn_global_load_lds((const unsigned*)((const char*)(gbase) + (voff)[_i]), (LAS unsigned*)(lds + (bufoff) + ldsw + _i * 8192), 16, 0, 0); } while (0)
; #define PG8_LDA(dst, b, h) do { _Pragma("unroll") for (int m = 0; m < 4; ++m) _Pragma("unroll") for (int k = 0; k < 2; ++k) dst[m][k] = *(const LAS bf16x8*)(lds + PG8_SA(b, h) + aoff + m * 2048 + k * 1024); } while (0)
; #define PG8_LDB(dst, b, h) do { _Pragma("unroll") for (int n = 0; n < 2; ++n) _Pragma("unroll") for (int k = 0; k < 2; ++k) dst[n][k] = *(const LAS bf16x8*)(lds + PG8_SB(b, h) + boff + n * 2048 + k * 1024); } while (0)
; #define PG8_MMA(ai, bj, At, Bt) do { __builtin_amdgcn_s_setprio(1); _Pragma("unroll") for (int m = 0; m < 4; ++m) _Pragma("unroll") for (int n = 0; n < 2; ++n) _Pragma("unroll") for (int k = 0; k < 2; ++k) \
;         acc[ai][bj][m][n] = __builtin_amdgcn_mfma_f32_16x16x32_bf16(Bt[n][k], At[m][k], acc[ai][bj][m][n], 0, 0, 0); __builtin_amdgcn_s_setprio(0); } while (0)
; #define PG8_WAIT_V(n) asm volatile("s_waitcnt vmcnt(" #n ")" ::: "memory")
; #define PG8_WAIT_L(n) asm volatile("s_waitcnt lgkmcnt(" #n ")" ::: "memory")
; #define PG8_BAR __builtin_amdgcn_s_barrier()
; #define PG8_SCHED __builtin_amdgcn_sched_barrier(0)
; template <class Epi, class Sched>
; __device__ __forceinline__ void gemm_phase(LAS unsigned char* lds, const Gemm g, const Sched& S, const Epi& E) {
;     ...
;             PG8_STAGE(PG8_SB(0, 1), b2 + hstep, voffB);
;             PG8_WAIT_V(6); PG8_BAR; PG8_MMA(1, 1, At, B1); PG8_BAR;
;             PG8_LDB(B0, 1, 0); PG8_SCHED; PG8_LDA(At, 1, 0); PG8_STAGE(PG8_SA(0, 1), a2 + hstep, voffA);
;             PG8_WAIT_L(8); PG8_BAR; PG8_WAIT_L(0); PG8_MMA(0, 0, At, B0); PG8_BAR; PG8_SCHED;
;             PG8_LDB(B1, 1, 1); PG8_STAGE(PG8_SB(1, 0), b3, voffB);
;             PG8_BAR; PG8_WAIT_L(0); PG8_MMA(0, 1, At, B1); PG8_BAR;
;             PG8_LDA(At, 1, 1); PG8_STAGE(PG8_SA(1, 0), a3, voffA);
	s_add_u32 s48, s18, 0x40000
	s_addc_u32 s49, s19, 0
	s_add_i32 s47, s39, s25
	v_lshl_add_u64 v[150:151], s[48:49], 0, v[132:133]
	s_mov_b32 m0, s47
	s_nop 0
	global_load_lds_dwordx4 v[150:151], off
	v_lshl_add_u64 v[150:151], s[48:49], 0, v[128:129]
	s_add_i32 m0, s47, 0x2000
	s_nop 0
	global_load_lds_dwordx4 v[150:151], off
	s_waitcnt vmcnt(6)
	s_barrier
	s_setprio 1
	v_mfma_f32_16x16x32_bf16 v[52:55], v[202:205], v[166:169], v[52:55]
	v_mfma_f32_16x16x32_bf16 v[48:51], v[210:213], v[166:169], v[48:51]
	v_mfma_f32_16x16x32_bf16 v[36:39], v[202:205], v[174:177], v[36:39]
	v_mfma_f32_16x16x32_bf16 v[32:35], v[210:213], v[174:177], v[32:35]
	v_mfma_f32_16x16x32_bf16 v[20:23], v[202:205], v[182:185], v[20:23]
	v_mfma_f32_16x16x32_bf16 v[16:19], v[210:213], v[182:185], v[16:19]
	v_mfma_f32_16x16x32_bf16 v[4:7], v[202:205], v[190:193], v[4:7]
	v_mfma_f32_16x16x32_bf16 v[0:3], v[210:213], v[190:193], v[0:3]
	v_mfma_f32_16x16x32_bf16 v[52:55], v[206:209], v[170:173], v[52:55]
	v_mfma_f32_16x16x32_bf16 v[48:51], v[214:217], v[170:173], v[48:51]
	v_mfma_f32_16x16x32_bf16 v[36:39], v[206:209], v[178:181], v[36:39]
	v_mfma_f32_16x16x32_bf16 v[32:35], v[214:217], v[178:181], v[32:35]
	v_mfma_f32_16x16x32_bf16 v[20:23], v[206:209], v[186:189], v[20:23]
	v_mfma_f32_16x16x32_bf16 v[16:19], v[214:217], v[186:189], v[16:19]
	v_mfma_f32_16x16x32_bf16 v[4:7], v[206:209], v[194:197], v[4:7]
	v_mfma_f32_16x16x32_bf16 v[0:3], v[214:217], v[194:197], v[0:3]
	s_setprio 0
	s_add_i32 s47, 0, 0x18000
	v_add_u32_e32 v162, s47, v146
	s_barrier
	ds_read_b128 v[150:153], v162
	ds_read_b128 v[154:157], v162 offset:1024
	ds_read_b128 v[158:161], v162 offset:2048
	ds_read_b128 v[162:165], v162 offset:3072
	s_add_u32 s20, s20, 0x40000
	s_addc_u32 s21, s21, 0
	s_mov_b32 m0, s29
	v_lshl_add_u64 v[202:203], s[20:21], 0, v[134:135]
	ds_read_b128 v[166:169], v148 offset:32768
	ds_read_b128 v[170:173], v148 offset:33792
	ds_read_b128 v[174:177], v148 offset:34816
	ds_read_b128 v[178:181], v148 offset:35840
	ds_read_b128 v[182:185], v148 offset:36864
	ds_read_b128 v[186:189], v148 offset:37888
	ds_read_b128 v[190:193], v148 offset:38912
	ds_read_b128 v[194:197], v148 offset:39936
	global_load_lds_dwordx4 v[202:203], off
	v_lshl_add_u64 v[202:203], s[20:21], 0, v[130:131]
	s_mov_b32 m0, s30
	s_nop 0
	global_load_lds_dwordx4 v[202:203], off
	s_waitcnt lgkmcnt(8)
	s_barrier
	s_waitcnt lgkmcnt(0)
	s_setprio 1
	s_waitcnt lgkmcnt(0)
	v_mfma_f32_16x16x32_bf16 v[124:127], v[150:153], v[166:169], v[124:127]
	v_mfma_f32_16x16x32_bf16 v[116:119], v[158:161], v[166:169], v[116:119]
	v_mfma_f32_16x16x32_bf16 v[108:111], v[150:153], v[174:177], v[108:111]
	v_mfma_f32_16x16x32_bf16 v[100:103], v[158:161], v[174:177], v[100:103]
	v_mfma_f32_16x16x32_bf16 v[92:95], v[150:153], v[182:185], v[92:95]
	v_mfma_f32_16x16x32_bf16 v[84:87], v[158:161], v[182:185], v[84:87]
	v_mfma_f32_16x16x32_bf16 v[76:79], v[150:153], v[190:193], v[76:79]
	v_mfma_f32_16x16x32_bf16 v[68:71], v[158:161], v[190:193], v[68:71]
	v_mfma_f32_16x16x32_bf16 v[124:127], v[154:157], v[170:173], v[124:127]
	v_mfma_f32_16x16x32_bf16 v[116:119], v[162:165], v[170:173], v[116:119]
	v_mfma_f32_16x16x32_bf16 v[108:111], v[154:157], v[178:181], v[108:111]
	v_mfma_f32_16x16x32_bf16 v[100:103], v[162:165], v[178:181], v[100:103]
	v_mfma_f32_16x16x32_bf16 v[92:95], v[154:157], v[186:189], v[92:95]
	v_mfma_f32_16x16x32_bf16 v[84:87], v[162:165], v[186:189], v[84:87]
	v_mfma_f32_16x16x32_bf16 v[76:79], v[154:157], v[194:197], v[76:79]
	v_mfma_f32_16x16x32_bf16 v[68:71], v[162:165], v[194:197], v[68:71]
	s_setprio 0
	s_barrier
	s_add_i32 s20, 0, 0x1c000
	s_add_i32 s21, s47, s25
	v_add_u32_e32 v214, s20, v146
	v_lshl_add_u64 v[198:199], v[198:199], 0, s[0:1]
	s_mov_b32 m0, s21
	ds_read_b128 v[202:205], v214
	ds_read_b128 v[206:209], v214 offset:1024
	ds_read_b128 v[210:213], v214 offset:2048
	ds_read_b128 v[214:217], v214 offset:3072
	global_load_lds_dwordx4 v[198:199], off
	v_lshl_add_u64 v[198:199], v[218:219], 0, s[0:1]
	s_add_i32 m0, s21, 0x2000
	s_nop 0
	global_load_lds_dwordx4 v[198:199], off
	s_barrier
	s_waitcnt lgkmcnt(0)
	s_setprio 1
	s_waitcnt lgkmcnt(0)
	v_mfma_f32_16x16x32_bf16 v[120:123], v[202:205], v[166:169], v[120:123]
	v_mfma_f32_16x16x32_bf16 v[112:115], v[210:213], v[166:169], v[112:115]
	v_mfma_f32_16x16x32_bf16 v[104:107], v[202:205], v[174:177], v[104:107]
	v_mfma_f32_16x16x32_bf16 v[96:99], v[210:213], v[174:177], v[96:99]
	v_mfma_f32_16x16x32_bf16 v[88:91], v[202:205], v[182:185], v[88:91]
	v_mfma_f32_16x16x32_bf16 v[80:83], v[210:213], v[182:185], v[80:83]
	v_mfma_f32_16x16x32_bf16 v[72:75], v[202:205], v[190:193], v[72:75]
	v_mfma_f32_16x16x32_bf16 v[64:67], v[210:213], v[190:193], v[64:67]
	v_mfma_f32_16x16x32_bf16 v[120:123], v[206:209], v[170:173], v[120:123]
	v_mfma_f32_16x16x32_bf16 v[112:115], v[214:217], v[170:173], v[112:115]
	v_mfma_f32_16x16x32_bf16 v[104:107], v[206:209], v[178:181], v[104:107]
	v_mfma_f32_16x16x32_bf16 v[96:99], v[214:217], v[178:181], v[96:99]
	v_mfma_f32_16x16x32_bf16 v[88:91], v[206:209], v[186:189], v[88:91]
	v_mfma_f32_16x16x32_bf16 v[80:83], v[214:217], v[186:189], v[80:83]
	v_mfma_f32_16x16x32_bf16 v[72:75], v[206:209], v[194:197], v[72:75]
	v_mfma_f32_16x16x32_bf16 v[64:67], v[214:217], v[194:197], v[64:67]
	s_setprio 0
	s_mov_b32 m0, s35
	v_lshl_add_u64 v[198:199], v[220:221], 0, s[0:1]
	s_barrier
	ds_read_b128 v[166:169], v148 offset:49152
	ds_read_b128 v[170:173], v148 offset:50176
	ds_read_b128 v[174:177], v148 offset:51200
	ds_read_b128 v[178:181], v148 offset:52224
	ds_read_b128 v[182:185], v148 offset:53248
	ds_read_b128 v[186:189], v148 offset:54272
	ds_read_b128 v[190:193], v148 offset:55296
	ds_read_b128 v[194:197], v148 offset:56320
	global_load_lds_dwordx4 v[198:199], off
	v_lshl_add_u64 v[198:199], v[222:223], 0, s[0:1]
	s_mov_b32 m0, s36
	s_nop 0
	global_load_lds_dwordx4 v[198:199], off
	s_barrier
; __device__ __forceinline__ unsigned cvt_pk_bf16(float lo, float hi) { unsigned r; asm volatile("v_cvt_pk_bf16_f32 %0, %1, %2" : "=v"(r) : "v"(lo), "v"(hi)); return r; }
; __device__ __forceinline__ float silu_f(float a) { return a * __builtin_amdgcn_rcpf(1.0f + __expf(-a)); }
; #define PG8_STAGE(bufoff, gbase, voff) do { _Pragma("unroll") for (int _i = 0; _i < 2; ++_i) \
;         __builtin_amdgcn_global_load_lds((const unsigned*)((const char*)(gbase) + (voff)[_i]), (LAS unsigned*)(lds + (bufoff) + ldsw + _i * 8192), 16, 0, 0); } while (0)
; #define PG8_MMA(ai, bj, At, Bt) do { __builtin_amdgcn_s_setprio(1); _Pragma("unroll") for (int m = 0; m < 4; ++m) _Pragma("unroll") for (int n = 0; n < 2; ++n) _Pragma("unroll") for (int k = 0; k < 2; ++k) \
;         acc[ai][bj][m][n] = __builtin_amdgcn_mfma_f32_16x16x32_bf16(Bt[n][k], At[m][k], acc[ai][bj][m][n], 0, 0, 0); __builtin_amdgcn_s_setprio(0); } while (0)
; #define PG8_WAIT_V(n) asm volatile("s_waitcnt vmcnt(" #n ")" ::: "memory")
; #define PG8_WAIT_L(n) asm volatile("s_waitcnt lgkmcnt(" #n ")" ::: "memory")
; template <class Epi, class Sched>
; __device__ __forceinline__ void gemm_phase(LAS unsigned char* lds, const Gemm g, const Sched& S, const Epi& E) {
;     ...
;             PG8_BAR; PG8_WAIT_L(0); PG8_MMA(1, 0, At, B0); PG8_BAR; PG8_SCHED;
;             PG8_STAGE(PG8_SB(1, 1), b3 + hstep, voffB);
;             PG8_WAIT_V(6); PG8_BAR; PG8_MMA(1, 1, At, B1); PG8_BAR;
;         }
;         E(acc, cur, wr, wc, fr, fq);
;         if (!has_next) break;
;     __device__ __forceinline__ void operator()(const AccT& acc, const Unit& u, int wr, int wc, int fr, int fq) const {
;     ...
;         const int row0 = u.pm * 256 + wr * 64 + fr, hc0 = u.pn * 128 + wc * 32 + 8 * fq;
; #pragma unroll
;         for (int ai = 0; ai < 2; ++ai)
; #pragma unroll
;             for (int m = 0; m < 4; ++m) {
;                 const f32x4 a0 = acc[ai][0][m][0], a1 = acc[ai][0][m][1], b0 = acc[ai][1][m][0], b1 = acc[ai][1][m][1];
;                 u32x4 w;
;                 w.x = cvt_pk_bf16(silu_f(a0[0]) * b0[0], silu_f(a0[1]) * b0[1]); w.y = cvt_pk_bf16(silu_f(a0[2]) * b0[2], silu_f(a0[3]) * b0[3]);
;                 w.z = cvt_pk_bf16(silu_f(a1[0]) * b1[0], silu_f(a1[1]) * b1[1]); w.w = cvt_pk_bf16(silu_f(a1[2]) * b1[2], silu_f(a1[3]) * b1[3]);
;                 *(u32x4*)(H + (size_t)(row0 + ai * 128 + m * 16) * DFF + hc0) = w;
	s_waitcnt lgkmcnt(0)
	s_setprio 1
	s_waitcnt lgkmcnt(0)
	v_mfma_f32_16x16x32_bf16 v[60:63], v[150:153], v[166:169], v[60:63]
	v_mfma_f32_16x16x32_bf16 v[56:59], v[158:161], v[166:169], v[56:59]
	v_mfma_f32_16x16x32_bf16 v[44:47], v[150:153], v[174:177], v[44:47]
	v_mfma_f32_16x16x32_bf16 v[40:43], v[158:161], v[174:177], v[40:43]
	v_mfma_f32_16x16x32_bf16 v[28:31], v[150:153], v[182:185], v[28:31]
	v_mfma_f32_16x16x32_bf16 v[24:27], v[158:161], v[182:185], v[24:27]
	v_mfma_f32_16x16x32_bf16 v[12:15], v[150:153], v[190:193], v[12:15]
	v_mfma_f32_16x16x32_bf16 v[8:11], v[158:161], v[190:193], v[8:11]
	v_mfma_f32_16x16x32_bf16 v[60:63], v[154:157], v[170:173], v[60:63]
	v_mfma_f32_16x16x32_bf16 v[56:59], v[162:165], v[170:173], v[56:59]
	v_mfma_f32_16x16x32_bf16 v[44:47], v[154:157], v[178:181], v[44:47]
	v_mfma_f32_16x16x32_bf16 v[40:43], v[162:165], v[178:181], v[40:43]
	v_mfma_f32_16x16x32_bf16 v[28:31], v[154:157], v[186:189], v[28:31]
	v_mfma_f32_16x16x32_bf16 v[24:27], v[162:165], v[186:189], v[24:27]
	v_mfma_f32_16x16x32_bf16 v[12:15], v[154:157], v[194:197], v[12:15]
	v_mfma_f32_16x16x32_bf16 v[8:11], v[162:165], v[194:197], v[8:11]
	s_setprio 0
	s_barrier
	s_add_u32 s18, s18, 0x40080
	s_addc_u32 s19, s19, 0
	s_add_i32 s20, s20, s25
	v_lshl_add_u64 v[150:151], s[18:19], 0, v[132:133]
	s_mov_b32 m0, s20
	s_nop 0
	global_load_lds_dwordx4 v[150:151], off
	v_lshl_add_u64 v[150:151], s[18:19], 0, v[128:129]
	s_add_i32 m0, s20, 0x2000
	s_nop 0
	global_load_lds_dwordx4 v[150:151], off
	s_waitcnt vmcnt(6)
	s_barrier
	s_setprio 1
	v_mfma_f32_16x16x32_bf16 v[52:55], v[202:205], v[166:169], v[52:55]
	v_mfma_f32_16x16x32_bf16 v[48:51], v[210:213], v[166:169], v[48:51]
	v_mfma_f32_16x16x32_bf16 v[36:39], v[202:205], v[174:177], v[36:39]
	v_mfma_f32_16x16x32_bf16 v[32:35], v[210:213], v[174:177], v[32:35]
	v_mfma_f32_16x16x32_bf16 v[20:23], v[202:205], v[182:185], v[20:23]
	v_mfma_f32_16x16x32_bf16 v[16:19], v[210:213], v[182:185], v[16:19]
	v_mfma_f32_16x16x32_bf16 v[4:7], v[202:205], v[190:193], v[4:7]
	v_mfma_f32_16x16x32_bf16 v[0:3], v[210:213], v[190:193], v[0:3]
	v_mfma_f32_16x16x32_bf16 v[52:55], v[206:209], v[170:173], v[52:55]
	v_mfma_f32_16x16x32_bf16 v[48:51], v[214:217], v[170:173], v[48:51]
	v_mfma_f32_16x16x32_bf16 v[36:39], v[206:209], v[178:181], v[36:39]
	v_mfma_f32_16x16x32_bf16 v[32:35], v[214:217], v[178:181], v[32:35]
	v_mfma_f32_16x16x32_bf16 v[20:23], v[206:209], v[186:189], v[20:23]
	v_mfma_f32_16x16x32_bf16 v[16:19], v[214:217], v[186:189], v[16:19]
	v_mfma_f32_16x16x32_bf16 v[4:7], v[206:209], v[194:197], v[4:7]
	v_mfma_f32_16x16x32_bf16 v[0:3], v[214:217], v[194:197], v[0:3]
	s_setprio 0
	s_add_i32 s46, s46, 2
	s_add_u32 s16, s16, 0x100
	s_addc_u32 s17, s17, 0
	s_add_u32 s44, s44, 0x100
	s_addc_u32 s45, s45, 0
	s_cmp_gt_u32 s46, 13
	s_barrier
	s_cbranch_scc0 .LBB0_1021
	v_mov_b32_e32 v150, v144
	v_mov_b32_e32 v151, v145
	s_lshl_b32 s5, s14, 8
	s_add_i32 s5, s5, s33
	v_add_u32_e32 v150, s5, v150
	s_lshl_b32 s5, s41, 7
	s_or_b32 s5, s5, s34
	v_lshl_add_u32 v152, v151, 3, s5
	v_ashrrev_i32_e32 v153, 31, v152
	v_mov_b64_e32 v[154:155], s[82:83]
	v_lshlrev_b64 v[156:157], 1, v[152:153]
	v_mov_b32_e32 v158, 0xbfb8aa3b
	v_mov_b32_e32 v159, 0xbfb8aa3b
	v_mov_b32_e32 v160, 1.0
	v_mov_b32_e32 v161, 1.0
	v_pk_mul_f32 v[162:163], v[124:125], v[158:159]
	v_pk_mul_f32 v[164:165], v[126:127], v[158:159]
	v_pk_mul_f32 v[166:167], v[116:117], v[158:159]
	v_pk_mul_f32 v[168:169], v[118:119], v[158:159]
	v_pk_mul_f32 v[170:171], v[108:109], v[158:159]
	v_pk_mul_f32 v[172:173], v[110:111], v[158:159]
	v_pk_mul_f32 v[174:175], v[100:101], v[158:159]
	v_pk_mul_f32 v[176:177], v[102:103], v[158:159]
	v_exp_f32_e32 v162, v162
	v_exp_f32_e32 v163, v163
	v_exp_f32_e32 v164, v164
	v_exp_f32_e32 v165, v165
	v_exp_f32_e32 v166, v166
	v_exp_f32_e32 v167, v167
	v_exp_f32_e32 v168, v168
	v_exp_f32_e32 v169, v169
	v_exp_f32_e32 v170, v170
	v_exp_f32_e32 v171, v171
	v_exp_f32_e32 v172, v172
	v_exp_f32_e32 v173, v173
	v_exp_f32_e32 v174, v174
	v_exp_f32_e32 v175, v175
	v_exp_f32_e32 v176, v176
	v_exp_f32_e32 v177, v177
	v_pk_add_f32 v[162:163], v[162:163], v[160:161]
	v_pk_add_f32 v[164:165], v[164:165], v[160:161]
	v_pk_add_f32 v[166:167], v[166:167], v[160:161]
	v_pk_add_f32 v[168:169], v[168:169], v[160:161]
	v_pk_add_f32 v[170:171], v[170:171], v[160:161]
	v_pk_add_f32 v[172:173], v[172:173], v[160:161]
	v_pk_add_f32 v[174:175], v[174:175], v[160:161]
	v_pk_add_f32 v[176:177], v[176:177], v[160:161]
	v_rcp_f32_e32 v162, v162
	v_rcp_f32_e32 v163, v163
	v_rcp_f32_e32 v164, v164
	v_rcp_f32_e32 v165, v165
	v_rcp_f32_e32 v166, v166
	v_rcp_f32_e32 v167, v167
	v_rcp_f32_e32 v168, v168
	v_rcp_f32_e32 v169, v169
	v_rcp_f32_e32 v170, v170
	v_rcp_f32_e32 v171, v171
	v_rcp_f32_e32 v172, v172
	v_rcp_f32_e32 v173, v173
	v_rcp_f32_e32 v174, v174
	v_rcp_f32_e32 v175, v175
	v_rcp_f32_e32 v176, v176
	v_rcp_f32_e32 v177, v177
	v_mad_i64_i32 v[178:179], s[16:17], v150, s40, v[154:155]
	v_lshl_add_u64 v[178:179], v[178:179], 0, v[156:157]
	v_add_u32_e32 v195, 0x10, v150
	v_mad_i64_i32 v[180:181], s[16:17], v195, s40, v[154:155]
	v_lshl_add_u64 v[180:181], v[180:181], 0, v[156:157]
	v_pk_mul_f32 v[124:125], v[124:125], v[162:163]
	v_pk_mul_f32 v[126:127], v[126:127], v[164:165]
	v_pk_mul_f32 v[116:117], v[116:117], v[166:167]
	v_pk_mul_f32 v[118:119], v[118:119], v[168:169]
	v_pk_mul_f32 v[108:109], v[108:109], v[170:171]
	v_pk_mul_f32 v[110:111], v[110:111], v[172:173]
	v_pk_mul_f32 v[100:101], v[100:101], v[174:175]
	v_pk_mul_f32 v[102:103], v[102:103], v[176:177]
	v_pk_mul_f32 v[124:125], v[124:125], v[120:121]
	v_pk_mul_f32 v[126:127], v[126:127], v[122:123]
; __device__ __forceinline__ unsigned cvt_pk_bf16(float lo, float hi) { unsigned r; asm volatile("v_cvt_pk_bf16_f32 %0, %1, %2" : "=v"(r) : "v"(lo), "v"(hi)); return r; }
; __device__ __forceinline__ float silu_f(float a) { return a * __builtin_amdgcn_rcpf(1.0f + __expf(-a)); }
;     __device__ __forceinline__ void operator()(const AccT& acc, const Unit& u, int wr, int wc, int fr, int fq) const {
;     ...
;                 const f32x4 a0 = acc[ai][0][m][0], a1 = acc[ai][0][m][1], b0 = acc[ai][1][m][0], b1 = acc[ai][1][m][1];
;                 u32x4 w;
;                 w.x = cvt_pk_bf16(silu_f(a0[0]) * b0[0], silu_f(a0[1]) * b0[1]); w.y = cvt_pk_bf16(silu_f(a0[2]) * b0[2], silu_f(a0[3]) * b0[3]);
;                 w.z = cvt_pk_bf16(silu_f(a1[0]) * b1[0], silu_f(a1[1]) * b1[1]); w.w = cvt_pk_bf16(silu_f(a1[2]) * b1[2], silu_f(a1[3]) * b1[3]);
;                 *(u32x4*)(H + (size_t)(row0 + ai * 128 + m * 16) * DFF + hc0) = w;
	v_pk_mul_f32 v[116:117], v[116:117], v[112:113]
	v_pk_mul_f32 v[118:119], v[118:119], v[114:115]
	v_pk_mul_f32 v[108:109], v[108:109], v[104:105]
	v_pk_mul_f32 v[110:111], v[110:111], v[106:107]
	v_pk_mul_f32 v[100:101], v[100:101], v[96:97]
	v_pk_mul_f32 v[102:103], v[102:103], v[98:99]
	v_cvt_pk_bf16_f32 v120, v124, v125
	v_cvt_pk_bf16_f32 v121, v126, v127
	v_cvt_pk_bf16_f32 v122, v116, v117
	v_cvt_pk_bf16_f32 v123, v118, v119
	global_store_dwordx4 v[178:179], v[120:123], off
	v_cvt_pk_bf16_f32 v104, v108, v109
	v_cvt_pk_bf16_f32 v105, v110, v111
	v_cvt_pk_bf16_f32 v106, v100, v101
	v_cvt_pk_bf16_f32 v107, v102, v103
	global_store_dwordx4 v[180:181], v[104:107], off
	v_pk_mul_f32 v[162:163], v[92:93], v[158:159]
	v_pk_mul_f32 v[164:165], v[94:95], v[158:159]
	v_pk_mul_f32 v[166:167], v[84:85], v[158:159]
	v_pk_mul_f32 v[168:169], v[86:87], v[158:159]
	v_pk_mul_f32 v[170:171], v[76:77], v[158:159]
	v_pk_mul_f32 v[172:173], v[78:79], v[158:159]
	v_pk_mul_f32 v[174:175], v[68:69], v[158:159]
	v_pk_mul_f32 v[176:177], v[70:71], v[158:159]
	v_exp_f32_e32 v162, v162
	v_exp_f32_e32 v163, v163
	v_exp_f32_e32 v164, v164
	v_exp_f32_e32 v165, v165
	v_exp_f32_e32 v166, v166
	v_exp_f32_e32 v167, v167
	v_exp_f32_e32 v168, v168
	v_exp_f32_e32 v169, v169
	v_exp_f32_e32 v170, v170
	v_exp_f32_e32 v171, v171
	v_exp_f32_e32 v172, v172
	v_exp_f32_e32 v173, v173
	v_exp_f32_e32 v174, v174
	v_exp_f32_e32 v175, v175
	v_exp_f32_e32 v176, v176
	v_exp_f32_e32 v177, v177
	v_pk_add_f32 v[162:163], v[162:163], v[160:161]
	v_pk_add_f32 v[164:165], v[164:165], v[160:161]
	v_pk_add_f32 v[166:167], v[166:167], v[160:161]
	v_pk_add_f32 v[168:169], v[168:169], v[160:161]
	v_pk_add_f32 v[170:171], v[170:171], v[160:161]
	v_pk_add_f32 v[172:173], v[172:173], v[160:161]
	v_pk_add_f32 v[174:175], v[174:175], v[160:161]
	v_pk_add_f32 v[176:177], v[176:177], v[160:161]
	v_rcp_f32_e32 v162, v162
	v_rcp_f32_e32 v163, v163
	v_rcp_f32_e32 v164, v164
	v_rcp_f32_e32 v165, v165
	v_rcp_f32_e32 v166, v166
	v_rcp_f32_e32 v167, v167
	v_rcp_f32_e32 v168, v168
	v_rcp_f32_e32 v169, v169
	v_rcp_f32_e32 v170, v170
	v_rcp_f32_e32 v171, v171
	v_rcp_f32_e32 v172, v172
	v_rcp_f32_e32 v173, v173
	v_rcp_f32_e32 v174, v174
	v_rcp_f32_e32 v175, v175
	v_rcp_f32_e32 v176, v176
	v_rcp_f32_e32 v177, v177
	v_add_u32_e32 v196, 0x20, v150
	v_mad_i64_i32 v[182:183], s[16:17], v196, s40, v[154:155]
	v_lshl_add_u64 v[182:183], v[182:183], 0, v[156:157]
	v_add_u32_e32 v197, 0x30, v150
	v_mad_i64_i32 v[184:185], s[16:17], v197, s40, v[154:155]
	v_lshl_add_u64 v[184:185], v[184:185], 0, v[156:157]
	v_pk_mul_f32 v[92:93], v[92:93], v[162:163]
	v_pk_mul_f32 v[94:95], v[94:95], v[164:165]
	v_pk_mul_f32 v[84:85], v[84:85], v[166:167]
	v_pk_mul_f32 v[86:87], v[86:87], v[168:169]
	v_pk_mul_f32 v[76:77], v[76:77], v[170:171]
	v_pk_mul_f32 v[78:79], v[78:79], v[172:173]
	v_pk_mul_f32 v[68:69], v[68:69], v[174:175]
	v_pk_mul_f32 v[70:71], v[70:71], v[176:177]
	v_pk_mul_f32 v[92:93], v[92:93], v[88:89]
	v_pk_mul_f32 v[94:95], v[94:95], v[90:91]
	v_pk_mul_f32 v[84:85], v[84:85], v[80:81]
	v_pk_mul_f32 v[86:87], v[86:87], v[82:83]
	v_pk_mul_f32 v[76:77], v[76:77], v[72:73]
	v_pk_mul_f32 v[78:79], v[78:79], v[74:75]
	v_pk_mul_f32 v[68:69], v[68:69], v[64:65]
	v_pk_mul_f32 v[70:71], v[70:71], v[66:67]
	v_cvt_pk_bf16_f32 v88, v92, v93
	v_cvt_pk_bf16_f32 v89, v94, v95
	v_cvt_pk_bf16_f32 v90, v84, v85
	v_cvt_pk_bf16_f32 v91, v86, v87
	global_store_dwordx4 v[182:183], v[88:91], off
	v_cvt_pk_bf16_f32 v72, v76, v77
	v_cvt_pk_bf16_f32 v73, v78, v79
	v_cvt_pk_bf16_f32 v74, v68, v69
	v_cvt_pk_bf16_f32 v75, v70, v71
	global_store_dwordx4 v[184:185], v[72:75], off
	v_pk_mul_f32 v[162:163], v[60:61], v[158:159]
	v_pk_mul_f32 v[164:165], v[62:63], v[158:159]
	v_pk_mul_f32 v[166:167], v[56:57], v[158:159]
	v_pk_mul_f32 v[168:169], v[58:59], v[158:159]
	v_pk_mul_f32 v[170:171], v[44:45], v[158:159]
	v_pk_mul_f32 v[172:173], v[46:47], v[158:159]
	v_pk_mul_f32 v[174:175], v[40:41], v[158:159]
	v_pk_mul_f32 v[176:177], v[42:43], v[158:159]
	v_exp_f32_e32 v162, v162
	v_exp_f32_e32 v163, v163
	v_exp_f32_e32 v164, v164
	v_exp_f32_e32 v165, v165
	v_exp_f32_e32 v166, v166
	v_exp_f32_e32 v167, v167
	v_exp_f32_e32 v168, v168
	v_exp_f32_e32 v169, v169
	v_exp_f32_e32 v170, v170
	v_exp_f32_e32 v171, v171
	v_exp_f32_e32 v172, v172
	v_exp_f32_e32 v173, v173
	v_exp_f32_e32 v174, v174
	v_exp_f32_e32 v175, v175
	v_exp_f32_e32 v176, v176
	v_exp_f32_e32 v177, v177
	v_pk_add_f32 v[162:163], v[162:163], v[160:161]
	v_pk_add_f32 v[164:165], v[164:165], v[160:161]
	v_pk_add_f32 v[166:167], v[166:167], v[160:161]
	v_pk_add_f32 v[168:169], v[168:169], v[160:161]
	v_pk_add_f32 v[170:171], v[170:171], v[160:161]
	v_pk_add_f32 v[172:173], v[172:173], v[160:161]
	v_pk_add_f32 v[174:175], v[174:175], v[160:161]
	v_pk_add_f32 v[176:177], v[176:177], v[160:161]
	v_rcp_f32_e32 v162, v162
	v_rcp_f32_e32 v163, v163
; __device__ __forceinline__ unsigned cvt_pk_bf16(float lo, float hi) { unsigned r; asm volatile("v_cvt_pk_bf16_f32 %0, %1, %2" : "=v"(r) : "v"(lo), "v"(hi)); return r; }
; __device__ __forceinline__ float silu_f(float a) { return a * __builtin_amdgcn_rcpf(1.0f + __expf(-a)); }
; #define PG8_WAIT_V(n) asm volatile("s_waitcnt vmcnt(" #n ")" ::: "memory")
; #define PG8_BAR __builtin_amdgcn_s_barrier()
; template <class Epi, class Sched>
; __device__ __forceinline__ void gemm_phase(LAS unsigned char* lds, const Gemm g, const Sched& S, const Epi& E) {
;     ...
;         if (!has_next) break;
; #pragma unroll
;         for (int a = 0; a < 2; ++a)
; #pragma unroll
;             for (int b = 0; b < 2; ++b)
; #pragma unroll
;                 for (int m = 0; m < 4; ++m)
; #pragma unroll
;                     for (int n = 0; n < 2; ++n) acc[a][b][m][n] = (f32x4){0.f, 0.f, 0.f, 0.f};
;         cur = nxt; cA = nA; cB = nB; ++ui;
;     }
;     PG8_WAIT_V(0);
;     if (wr == 0) PG8_BAR;
;     PG8_BAR;
;     __device__ __forceinline__ void operator()(const AccT& acc, const Unit& u, int wr, int wc, int fr, int fq) const {
;     ...
;                 const f32x4 a0 = acc[ai][0][m][0], a1 = acc[ai][0][m][1], b0 = acc[ai][1][m][0], b1 = acc[ai][1][m][1];
;                 u32x4 w;
;                 w.x = cvt_pk_bf16(silu_f(a0[0]) * b0[0], silu_f(a0[1]) * b0[1]); w.y = cvt_pk_bf16(silu_f(a0[2]) * b0[2], silu_f(a0[3]) * b0[3]);
;                 w.z = cvt_pk_bf16(silu_f(a1[0]) * b1[0], silu_f(a1[1]) * b1[1]); w.w = cvt_pk_bf16(silu_f(a1[2]) * b1[2], silu_f(a1[3]) * b1[3]);
;                 *(u32x4*)(H + (size_t)(row0 + ai * 128 + m * 16) * DFF + hc0) = w;
	v_rcp_f32_e32 v164, v164
	v_rcp_f32_e32 v165, v165
	v_rcp_f32_e32 v166, v166
	v_rcp_f32_e32 v167, v167
	v_rcp_f32_e32 v168, v168
	v_rcp_f32_e32 v169, v169
	v_rcp_f32_e32 v170, v170
	v_rcp_f32_e32 v171, v171
	v_rcp_f32_e32 v172, v172
	v_rcp_f32_e32 v173, v173
	v_rcp_f32_e32 v174, v174
	v_rcp_f32_e32 v175, v175
	v_rcp_f32_e32 v176, v176
	v_rcp_f32_e32 v177, v177
	v_add_u32_e32 v198, 0x80, v150
	v_mad_i64_i32 v[186:187], s[16:17], v198, s40, v[154:155]
	v_lshl_add_u64 v[186:187], v[186:187], 0, v[156:157]
	v_add_u32_e32 v199, 0x90, v150
	v_mad_i64_i32 v[188:189], s[16:17], v199, s40, v[154:155]
	v_lshl_add_u64 v[188:189], v[188:189], 0, v[156:157]
	v_pk_mul_f32 v[60:61], v[60:61], v[162:163]
	v_pk_mul_f32 v[62:63], v[62:63], v[164:165]
	v_pk_mul_f32 v[56:57], v[56:57], v[166:167]
	v_pk_mul_f32 v[58:59], v[58:59], v[168:169]
	v_pk_mul_f32 v[44:45], v[44:45], v[170:171]
	v_pk_mul_f32 v[46:47], v[46:47], v[172:173]
	v_pk_mul_f32 v[40:41], v[40:41], v[174:175]
	v_pk_mul_f32 v[42:43], v[42:43], v[176:177]
	v_pk_mul_f32 v[60:61], v[60:61], v[52:53]
	v_pk_mul_f32 v[62:63], v[62:63], v[54:55]
	v_pk_mul_f32 v[56:57], v[56:57], v[48:49]
	v_pk_mul_f32 v[58:59], v[58:59], v[50:51]
	v_pk_mul_f32 v[44:45], v[44:45], v[36:37]
	v_pk_mul_f32 v[46:47], v[46:47], v[38:39]
	v_pk_mul_f32 v[40:41], v[40:41], v[32:33]
	v_pk_mul_f32 v[42:43], v[42:43], v[34:35]
	v_cvt_pk_bf16_f32 v52, v60, v61
	v_cvt_pk_bf16_f32 v53, v62, v63
	v_cvt_pk_bf16_f32 v54, v56, v57
	v_cvt_pk_bf16_f32 v55, v58, v59
	global_store_dwordx4 v[186:187], v[52:55], off
	v_cvt_pk_bf16_f32 v36, v44, v45
	v_cvt_pk_bf16_f32 v37, v46, v47
	v_cvt_pk_bf16_f32 v38, v40, v41
	v_cvt_pk_bf16_f32 v39, v42, v43
	global_store_dwordx4 v[188:189], v[36:39], off
	v_pk_mul_f32 v[162:163], v[28:29], v[158:159]
	v_pk_mul_f32 v[164:165], v[30:31], v[158:159]
	v_pk_mul_f32 v[166:167], v[24:25], v[158:159]
	v_pk_mul_f32 v[168:169], v[26:27], v[158:159]
	v_pk_mul_f32 v[170:171], v[12:13], v[158:159]
	v_pk_mul_f32 v[172:173], v[14:15], v[158:159]
	v_pk_mul_f32 v[174:175], v[8:9], v[158:159]
	v_pk_mul_f32 v[176:177], v[10:11], v[158:159]
	v_exp_f32_e32 v162, v162
	v_exp_f32_e32 v163, v163
	v_exp_f32_e32 v164, v164
	v_exp_f32_e32 v165, v165
	v_exp_f32_e32 v166, v166
	v_exp_f32_e32 v167, v167
	v_exp_f32_e32 v168, v168
	v_exp_f32_e32 v169, v169
	v_exp_f32_e32 v170, v170
	v_exp_f32_e32 v171, v171
	v_exp_f32_e32 v172, v172
	v_exp_f32_e32 v173, v173
	v_exp_f32_e32 v174, v174
	v_exp_f32_e32 v175, v175
	v_exp_f32_e32 v176, v176
	v_exp_f32_e32 v177, v177
	v_pk_add_f32 v[162:163], v[162:163], v[160:161]
	v_pk_add_f32 v[164:165], v[164:165], v[160:161]
	v_pk_add_f32 v[166:167], v[166:167], v[160:161]
	v_pk_add_f32 v[168:169], v[168:169], v[160:161]
	v_pk_add_f32 v[170:171], v[170:171], v[160:161]
	v_pk_add_f32 v[172:173], v[172:173], v[160:161]
	v_pk_add_f32 v[174:175], v[174:175], v[160:161]
	v_pk_add_f32 v[176:177], v[176:177], v[160:161]
	v_rcp_f32_e32 v162, v162
	v_rcp_f32_e32 v163, v163
	v_rcp_f32_e32 v164, v164
	v_rcp_f32_e32 v165, v165
	v_rcp_f32_e32 v166, v166
	v_rcp_f32_e32 v167, v167
	v_rcp_f32_e32 v168, v168
	v_rcp_f32_e32 v169, v169
	v_rcp_f32_e32 v170, v170
	v_rcp_f32_e32 v171, v171
	v_rcp_f32_e32 v172, v172
	v_rcp_f32_e32 v173, v173
	v_rcp_f32_e32 v174, v174
	v_rcp_f32_e32 v175, v175
	v_rcp_f32_e32 v176, v176
	v_rcp_f32_e32 v177, v177
	v_add_u32_e32 v202, 0xa0, v150
	v_mad_i64_i32 v[190:191], s[16:17], v202, s40, v[154:155]
	v_lshl_add_u64 v[190:191], v[190:191], 0, v[156:157]
	v_add_u32_e32 v203, 0xb0, v150
	v_mad_i64_i32 v[192:193], s[16:17], v203, s40, v[154:155]
	v_lshl_add_u64 v[192:193], v[192:193], 0, v[156:157]
	v_pk_mul_f32 v[28:29], v[28:29], v[162:163]
	v_pk_mul_f32 v[30:31], v[30:31], v[164:165]
	v_pk_mul_f32 v[24:25], v[24:25], v[166:167]
	v_pk_mul_f32 v[26:27], v[26:27], v[168:169]
	v_pk_mul_f32 v[12:13], v[12:13], v[170:171]
	v_pk_mul_f32 v[14:15], v[14:15], v[172:173]
	v_pk_mul_f32 v[8:9], v[8:9], v[174:175]
	v_pk_mul_f32 v[10:11], v[10:11], v[176:177]
	v_pk_mul_f32 v[28:29], v[28:29], v[20:21]
	v_pk_mul_f32 v[30:31], v[30:31], v[22:23]
	v_pk_mul_f32 v[24:25], v[24:25], v[16:17]
	v_pk_mul_f32 v[26:27], v[26:27], v[18:19]
	v_pk_mul_f32 v[12:13], v[12:13], v[4:5]
	v_pk_mul_f32 v[14:15], v[14:15], v[6:7]
	v_pk_mul_f32 v[8:9], v[8:9], v[0:1]
	v_pk_mul_f32 v[10:11], v[10:11], v[2:3]
	v_cvt_pk_bf16_f32 v20, v28, v29
	v_cvt_pk_bf16_f32 v21, v30, v31
	v_cvt_pk_bf16_f32 v22, v24, v25
	v_cvt_pk_bf16_f32 v23, v26, v27
	global_store_dwordx4 v[190:191], v[20:23], off
	v_cvt_pk_bf16_f32 v4, v12, v13
	v_cvt_pk_bf16_f32 v5, v14, v15
	v_cvt_pk_bf16_f32 v6, v8, v9
	v_cvt_pk_bf16_f32 v7, v10, v11
	s_and_b64 vcc, exec, s[2:3]
	s_mov_b32 s41, s4
	s_mov_b32 s14, s6
	s_mov_b64 s[18:19], s[12:13]
	s_mov_b64 s[16:17], s[10:11]
	global_store_dwordx4 v[192:193], v[4:7], off
	s_cbranch_vccz .LBB0_1018
	s_waitcnt vmcnt(0)
	s_cmpk_gt_u32 s22, 0xff
	s_cbranch_scc1 .LBB0_1025
	s_barrier
